# row-scale loads of the in-proj/sample GEMM epilogues hoisted (8 loads up front), removed loads replaced by s_nop 1 to keep store->VALU wait states
# speedup vs baseline: 1.0029x; 1.0029x over previous
.LBB0_147:
	v_lshl_add_u32 v148, s21, 8, v154
	v_lshl_add_u32 v144, s20, 8, v152
	v_ashrrev_i32_e32 v149, 31, v148
	v_mov_b64_e32 v[146:147], s[52:53]
	v_ashrrev_i32_e32 v145, 31, v144
	v_mad_i64_i32 v[150:151], s[20:21], v144, s44, v[146:147]
	v_lshlrev_b64 v[148:149], 1, v[148:149]
	v_lshl_add_u64 v[158:159], v[150:151], 0, v[148:149]
	v_lshl_add_u64 v[150:151], v[144:145], 2, s[88:89]
	global_load_dword v160, v[150:151], off
	global_load_dword v236, v[150:151], off offset:64
	global_load_dword v237, v[150:151], off offset:128
	global_load_dword v238, v[150:151], off offset:192
	global_load_dword v239, v[150:151], off offset:512
	global_load_dword v240, v[150:151], off offset:576
	global_load_dword v241, v[150:151], off offset:640
	global_load_dword v242, v[150:151], off offset:704
	s_andn2_b64 vcc, exec, s[0:1]
	s_waitcnt vmcnt(0)
	v_pk_mul_f32 v[126:127], v[126:127], v[160:161] op_sel_hi:[1,0]
	v_pk_mul_f32 v[124:125], v[124:125], v[160:161] op_sel_hi:[1,0]
	v_pk_mul_f32 v[162:163], v[122:123], v[160:161] op_sel_hi:[1,0]
	v_pk_mul_f32 v[122:123], v[120:121], v[160:161] op_sel_hi:[1,0]
	v_cvt_pk_bf16_f32 v120, v124, v125
	v_cvt_pk_bf16_f32 v121, v126, v127
	v_pk_mul_f32 v[116:117], v[116:117], v[160:161] op_sel_hi:[1,0]
	v_cvt_pk_bf16_f32 v122, v122, v123
	v_cvt_pk_bf16_f32 v123, v162, v163
	global_store_dwordx4 v[158:159], v[120:123], off
	v_pk_mul_f32 v[118:119], v[118:119], v[160:161] op_sel_hi:[1,0]
	s_nop 0
	v_pk_mul_f32 v[120:121], v[114:115], v[160:161] op_sel_hi:[1,0]
	v_pk_mul_f32 v[114:115], v[112:113], v[160:161] op_sel_hi:[1,0]
	v_cvt_pk_bf16_f32 v112, v116, v117
	v_cvt_pk_bf16_f32 v113, v118, v119
	s_nop 0
	v_cvt_pk_bf16_f32 v114, v114, v115
	v_cvt_pk_bf16_f32 v115, v120, v121
	global_store_dwordx4 v[158:159], v[112:115], off offset:256
	s_nop 1
	v_or_b32_e32 v112, 16, v144
	v_ashrrev_i32_e32 v113, 31, v112
	v_mad_i64_i32 v[114:115], s[20:21], v112, s44, v[146:147]
	v_lshl_add_u64 v[112:113], v[112:113], 2, s[88:89]
	s_nop 1
	v_lshl_add_u64 v[114:115], v[114:115], 0, v[148:149]
	s_nop 1
	v_mov_b32_e32 v112, v236
	v_pk_mul_f32 v[110:111], v[110:111], v[112:113] op_sel_hi:[1,0]
	v_pk_mul_f32 v[108:109], v[108:109], v[112:113] op_sel_hi:[1,0]
	v_pk_mul_f32 v[116:117], v[106:107], v[112:113] op_sel_hi:[1,0]
	v_pk_mul_f32 v[106:107], v[104:105], v[112:113] op_sel_hi:[1,0]
	v_cvt_pk_bf16_f32 v104, v108, v109
	v_cvt_pk_bf16_f32 v105, v110, v111
	v_pk_mul_f32 v[100:101], v[100:101], v[112:113] op_sel_hi:[1,0]
	v_cvt_pk_bf16_f32 v106, v106, v107
	v_cvt_pk_bf16_f32 v107, v116, v117
	global_store_dwordx4 v[114:115], v[104:107], off
	v_pk_mul_f32 v[102:103], v[102:103], v[112:113] op_sel_hi:[1,0]
	s_nop 0
	v_pk_mul_f32 v[104:105], v[98:99], v[112:113] op_sel_hi:[1,0]
	v_pk_mul_f32 v[98:99], v[96:97], v[112:113] op_sel_hi:[1,0]
	v_cvt_pk_bf16_f32 v96, v100, v101
	v_cvt_pk_bf16_f32 v97, v102, v103
	s_nop 0
	v_cvt_pk_bf16_f32 v98, v98, v99
	v_cvt_pk_bf16_f32 v99, v104, v105
	global_store_dwordx4 v[114:115], v[96:99], off offset:256
	s_nop 1
	v_or_b32_e32 v96, 32, v144
	v_ashrrev_i32_e32 v97, 31, v96
	v_mad_i64_i32 v[98:99], s[20:21], v96, s44, v[146:147]
	v_lshl_add_u64 v[96:97], v[96:97], 2, s[88:89]
	s_nop 1
	v_lshl_add_u64 v[98:99], v[98:99], 0, v[148:149]
	s_nop 1
	v_mov_b32_e32 v96, v237
	v_pk_mul_f32 v[94:95], v[94:95], v[96:97] op_sel_hi:[1,0]
	v_pk_mul_f32 v[92:93], v[92:93], v[96:97] op_sel_hi:[1,0]
	v_pk_mul_f32 v[100:101], v[90:91], v[96:97] op_sel_hi:[1,0]
	v_pk_mul_f32 v[90:91], v[88:89], v[96:97] op_sel_hi:[1,0]
	v_cvt_pk_bf16_f32 v88, v92, v93
	v_cvt_pk_bf16_f32 v89, v94, v95
	v_pk_mul_f32 v[84:85], v[84:85], v[96:97] op_sel_hi:[1,0]
	v_cvt_pk_bf16_f32 v90, v90, v91
	v_cvt_pk_bf16_f32 v91, v100, v101
	global_store_dwordx4 v[98:99], v[88:91], off
	v_pk_mul_f32 v[86:87], v[86:87], v[96:97] op_sel_hi:[1,0]
	s_nop 0
	v_pk_mul_f32 v[88:89], v[82:83], v[96:97] op_sel_hi:[1,0]
	v_pk_mul_f32 v[82:83], v[80:81], v[96:97] op_sel_hi:[1,0]
	v_cvt_pk_bf16_f32 v80, v84, v85
	v_cvt_pk_bf16_f32 v81, v86, v87
	s_nop 0
	v_cvt_pk_bf16_f32 v82, v82, v83
	v_cvt_pk_bf16_f32 v83, v88, v89
	global_store_dwordx4 v[98:99], v[80:83], off offset:256
	s_nop 1
	v_or_b32_e32 v80, 48, v144
	v_ashrrev_i32_e32 v81, 31, v80
	v_mad_i64_i32 v[82:83], s[20:21], v80, s44, v[146:147]
	v_lshl_add_u64 v[80:81], v[80:81], 2, s[88:89]
	s_nop 1
	v_lshl_add_u64 v[82:83], v[82:83], 0, v[148:149]
	s_nop 1
	v_mov_b32_e32 v80, v238
	v_pk_mul_f32 v[78:79], v[78:79], v[80:81] op_sel_hi:[1,0]
	v_pk_mul_f32 v[76:77], v[76:77], v[80:81] op_sel_hi:[1,0]
	v_pk_mul_f32 v[84:85], v[74:75], v[80:81] op_sel_hi:[1,0]
	v_pk_mul_f32 v[74:75], v[72:73], v[80:81] op_sel_hi:[1,0]
	v_cvt_pk_bf16_f32 v72, v76, v77
	v_cvt_pk_bf16_f32 v73, v78, v79
	v_pk_mul_f32 v[70:71], v[70:71], v[80:81] op_sel_hi:[1,0]
	v_cvt_pk_bf16_f32 v74, v74, v75
	v_cvt_pk_bf16_f32 v75, v84, v85
	global_store_dwordx4 v[82:83], v[72:75], off
	v_pk_mul_f32 v[68:69], v[68:69], v[80:81] op_sel_hi:[1,0]
	s_nop 0
	v_pk_mul_f32 v[72:73], v[66:67], v[80:81] op_sel_hi:[1,0]
	v_pk_mul_f32 v[66:67], v[64:65], v[80:81] op_sel_hi:[1,0]
	v_cvt_pk_bf16_f32 v64, v68, v69
	v_cvt_pk_bf16_f32 v65, v70, v71
	s_nop 0
	v_cvt_pk_bf16_f32 v66, v66, v67
	v_cvt_pk_bf16_f32 v67, v72, v73
	global_store_dwordx4 v[82:83], v[64:67], off offset:256
	s_nop 1
	s_nop 1
	v_mov_b32_e32 v66, v239
	v_pk_mul_f32 v[62:63], v[62:63], v[66:67] op_sel_hi:[1,0]
	v_add_u32_e32 v64, 0x80, v144
	v_mad_i64_i32 v[64:65], s[20:21], v64, s44, v[146:147]
	v_lshl_add_u64 v[64:65], v[64:65], 0, v[148:149]
	v_pk_mul_f32 v[60:61], v[60:61], v[66:67] op_sel_hi:[1,0]
	v_pk_mul_f32 v[68:69], v[58:59], v[66:67] op_sel_hi:[1,0]
	v_pk_mul_f32 v[58:59], v[56:57], v[66:67] op_sel_hi:[1,0]
	v_cvt_pk_bf16_f32 v56, v60, v61
	v_cvt_pk_bf16_f32 v57, v62, v63
	v_pk_mul_f32 v[54:55], v[54:55], v[66:67] op_sel_hi:[1,0]
	v_cvt_pk_bf16_f32 v58, v58, v59
	v_cvt_pk_bf16_f32 v59, v68, v69
	global_store_dwordx4 v[64:65], v[56:59], off
	v_pk_mul_f32 v[52:53], v[52:53], v[66:67] op_sel_hi:[1,0]
	s_nop 0
	v_pk_mul_f32 v[56:57], v[50:51], v[66:67] op_sel_hi:[1,0]
	v_pk_mul_f32 v[50:51], v[48:49], v[66:67] op_sel_hi:[1,0]
	v_cvt_pk_bf16_f32 v48, v52, v53
	v_cvt_pk_bf16_f32 v49, v54, v55
	s_nop 0
	v_cvt_pk_bf16_f32 v50, v50, v51
	v_cvt_pk_bf16_f32 v51, v56, v57
	global_store_dwordx4 v[64:65], v[48:51], off offset:256
	s_nop 1
	s_nop 1
	v_mov_b32_e32 v50, v240
	v_pk_mul_f32 v[46:47], v[46:47], v[50:51] op_sel_hi:[1,0]
	v_add_u32_e32 v48, 0x90, v144
	v_mad_i64_i32 v[48:49], s[20:21], v48, s44, v[146:147]
	v_lshl_add_u64 v[48:49], v[48:49], 0, v[148:149]
	v_pk_mul_f32 v[44:45], v[44:45], v[50:51] op_sel_hi:[1,0]
	v_pk_mul_f32 v[52:53], v[42:43], v[50:51] op_sel_hi:[1,0]
	v_pk_mul_f32 v[42:43], v[40:41], v[50:51] op_sel_hi:[1,0]
	v_cvt_pk_bf16_f32 v40, v44, v45
	v_cvt_pk_bf16_f32 v41, v46, v47
	v_pk_mul_f32 v[38:39], v[38:39], v[50:51] op_sel_hi:[1,0]
	v_cvt_pk_bf16_f32 v42, v42, v43
	v_cvt_pk_bf16_f32 v43, v52, v53
	global_store_dwordx4 v[48:49], v[40:43], off
	v_pk_mul_f32 v[36:37], v[36:37], v[50:51] op_sel_hi:[1,0]
	s_nop 0
	v_pk_mul_f32 v[40:41], v[34:35], v[50:51] op_sel_hi:[1,0]
	v_pk_mul_f32 v[34:35], v[32:33], v[50:51] op_sel_hi:[1,0]
	v_cvt_pk_bf16_f32 v32, v36, v37
	v_cvt_pk_bf16_f32 v33, v38, v39
	s_nop 0
	v_cvt_pk_bf16_f32 v34, v34, v35
	v_cvt_pk_bf16_f32 v35, v40, v41
	global_store_dwordx4 v[48:49], v[32:35], off offset:256
	s_nop 1
	s_nop 1
	v_mov_b32_e32 v34, v241
	v_pk_mul_f32 v[30:31], v[30:31], v[34:35] op_sel_hi:[1,0]
	v_add_u32_e32 v32, 0xa0, v144
	v_mad_i64_i32 v[32:33], s[20:21], v32, s44, v[146:147]
	v_lshl_add_u64 v[32:33], v[32:33], 0, v[148:149]
	v_pk_mul_f32 v[28:29], v[28:29], v[34:35] op_sel_hi:[1,0]
	v_pk_mul_f32 v[36:37], v[26:27], v[34:35] op_sel_hi:[1,0]
	v_pk_mul_f32 v[26:27], v[24:25], v[34:35] op_sel_hi:[1,0]
	v_cvt_pk_bf16_f32 v24, v28, v29
	v_cvt_pk_bf16_f32 v25, v30, v31
	v_pk_mul_f32 v[22:23], v[22:23], v[34:35] op_sel_hi:[1,0]
	v_cvt_pk_bf16_f32 v26, v26, v27
	v_cvt_pk_bf16_f32 v27, v36, v37
	global_store_dwordx4 v[32:33], v[24:27], off
	v_pk_mul_f32 v[20:21], v[20:21], v[34:35] op_sel_hi:[1,0]
	s_nop 0
	v_pk_mul_f32 v[24:25], v[18:19], v[34:35] op_sel_hi:[1,0]
	v_pk_mul_f32 v[18:19], v[16:17], v[34:35] op_sel_hi:[1,0]
	v_cvt_pk_bf16_f32 v16, v20, v21
	v_cvt_pk_bf16_f32 v17, v22, v23
	s_nop 0
	v_cvt_pk_bf16_f32 v18, v18, v19
	v_cvt_pk_bf16_f32 v19, v24, v25
	global_store_dwordx4 v[32:33], v[16:19], off offset:256
	s_nop 1
	s_nop 1
	v_mov_b32_e32 v18, v242
	v_pk_mul_f32 v[14:15], v[14:15], v[18:19] op_sel_hi:[1,0]
	v_add_u32_e32 v16, 0xb0, v144
	v_mad_i64_i32 v[16:17], s[20:21], v16, s44, v[146:147]
	v_lshl_add_u64 v[16:17], v[16:17], 0, v[148:149]
	v_pk_mul_f32 v[12:13], v[12:13], v[18:19] op_sel_hi:[1,0]
	v_pk_mul_f32 v[20:21], v[10:11], v[18:19] op_sel_hi:[1,0]
	v_pk_mul_f32 v[10:11], v[8:9], v[18:19] op_sel_hi:[1,0]
	v_cvt_pk_bf16_f32 v8, v12, v13
	v_cvt_pk_bf16_f32 v9, v14, v15
	s_mov_b64 s[20:21], -1
	v_cvt_pk_bf16_f32 v10, v10, v11
	v_cvt_pk_bf16_f32 v11, v20, v21
	global_store_dwordx4 v[16:17], v[8:11], off
	v_pk_mul_f32 v[6:7], v[6:7], v[18:19] op_sel_hi:[1,0]
	v_pk_mul_f32 v[4:5], v[4:5], v[18:19] op_sel_hi:[1,0]
	v_pk_mul_f32 v[8:9], v[2:3], v[18:19] op_sel_hi:[1,0]
	v_pk_mul_f32 v[2:3], v[0:1], v[18:19] op_sel_hi:[1,0]
	v_cvt_pk_bf16_f32 v0, v4, v5
	v_cvt_pk_bf16_f32 v1, v6, v7
	s_nop 0
	v_cvt_pk_bf16_f32 v2, v2, v3
	v_cvt_pk_bf16_f32 v3, v8, v9
	global_store_dwordx4 v[16:17], v[0:3], off offset:256
	s_cbranch_vccnz .LBB0_138
	s_andn2_b64 vcc, exec, s[6:7]
	s_cbranch_vccnz .LBB0_137
	s_barrier
	s_branch .LBB0_137

.LBB0_213:
	v_lshl_add_u32 v128, s4, 8, v141
	v_ashrrev_i32_e32 v129, 31, v128
	v_lshl_add_u64 v[130:131], v[128:129], 2, s[88:89]
	global_load_dword v136, v[130:131], off
	global_load_dword v236, v[130:131], off offset:64
	global_load_dword v237, v[130:131], off offset:128
	global_load_dword v238, v[130:131], off offset:192
	global_load_dword v239, v[130:131], off offset:512
	global_load_dword v240, v[130:131], off offset:576
	global_load_dword v241, v[130:131], off offset:640
	global_load_dword v242, v[130:131], off offset:704
	v_ashrrev_i32_e32 v129, 1, v140
	s_lshl_b32 s1, s0, 8
	v_readlane_b32 s4, v235, 37
	v_and_b32_e32 v129, -8, v129
	s_or_b32 s1, s4, s1
	v_add_u32_e32 v134, s1, v129
	s_movk_i32 s0, 0x1040
	v_mov_b64_e32 v[132:133], s[52:53]
	v_ashrrev_i32_e32 v135, 31, v134
	v_mad_i64_i32 v[138:139], s[4:5], v128, s0, v[132:133]
	v_or_b32_e32 v140, 16, v128
	v_lshlrev_b64 v[134:135], 1, v[134:135]
	v_ashrrev_i32_e32 v141, 31, v140
	v_lshl_add_u64 v[138:139], v[138:139], 0, v[134:135]
	v_lshl_add_u64 v[142:143], v[140:141], 2, s[88:89]
	s_movk_i32 s1, 0x80
	v_writelane_b32 v235, s1, 45
	s_waitcnt vmcnt(0)
	v_pk_mul_f32 v[126:127], v[126:127], v[136:137] op_sel_hi:[1,0]
	v_pk_mul_f32 v[124:125], v[124:125], v[136:137] op_sel_hi:[1,0]
	v_pk_mul_f32 v[122:123], v[122:123], v[136:137] op_sel_hi:[1,0]
	v_pk_mul_f32 v[120:121], v[120:121], v[136:137] op_sel_hi:[1,0]
	v_pk_mul_f32 v[118:119], v[118:119], v[136:137] op_sel_hi:[1,0]
	v_pk_mul_f32 v[116:117], v[116:117], v[136:137] op_sel_hi:[1,0]
	v_pk_mul_f32 v[144:145], v[114:115], v[136:137] op_sel_hi:[1,0]
	v_pk_mul_f32 v[136:137], v[112:113], v[136:137] op_sel_hi:[1,0]
	v_cvt_pk_bf16_f32 v112, v124, v125
	v_cvt_pk_bf16_f32 v113, v126, v127
	v_cvt_pk_bf16_f32 v114, v120, v121
	v_cvt_pk_bf16_f32 v115, v122, v123
	global_store_dwordx4 v[138:139], v[112:115], off
	s_nop 1
	v_cvt_pk_bf16_f32 v112, v116, v117
	v_cvt_pk_bf16_f32 v113, v118, v119
	v_cvt_pk_bf16_f32 v114, v136, v137
	v_cvt_pk_bf16_f32 v115, v144, v145
	global_store_dwordx4 v[138:139], v[112:115], off offset:256
	s_nop 1
	v_mad_i64_i32 v[116:117], s[4:5], v140, s0, v[132:133]
	v_or_b32_e32 v114, 32, v128
	v_ashrrev_i32_e32 v115, 31, v114
	v_lshl_add_u64 v[116:117], v[116:117], 0, v[134:135]
	v_lshl_add_u64 v[118:119], v[114:115], 2, s[88:89]
	s_nop 1
	v_mov_b32_e32 v112, v236
	v_pk_mul_f32 v[110:111], v[110:111], v[112:113] op_sel_hi:[1,0]
	v_pk_mul_f32 v[108:109], v[108:109], v[112:113] op_sel_hi:[1,0]
	v_pk_mul_f32 v[106:107], v[106:107], v[112:113] op_sel_hi:[1,0]
	v_pk_mul_f32 v[104:105], v[104:105], v[112:113] op_sel_hi:[1,0]
	v_pk_mul_f32 v[102:103], v[102:103], v[112:113] op_sel_hi:[1,0]
	v_pk_mul_f32 v[100:101], v[100:101], v[112:113] op_sel_hi:[1,0]
	v_pk_mul_f32 v[120:121], v[98:99], v[112:113] op_sel_hi:[1,0]
	v_pk_mul_f32 v[112:113], v[96:97], v[112:113] op_sel_hi:[1,0]
	v_cvt_pk_bf16_f32 v96, v108, v109
	v_cvt_pk_bf16_f32 v97, v110, v111
	v_cvt_pk_bf16_f32 v98, v104, v105
	v_cvt_pk_bf16_f32 v99, v106, v107
	global_store_dwordx4 v[116:117], v[96:99], off
	s_nop 1
	v_cvt_pk_bf16_f32 v96, v100, v101
	v_cvt_pk_bf16_f32 v97, v102, v103
	v_cvt_pk_bf16_f32 v98, v112, v113
	v_cvt_pk_bf16_f32 v99, v120, v121
	global_store_dwordx4 v[116:117], v[96:99], off offset:256
	s_nop 1
	v_mad_i64_i32 v[100:101], s[4:5], v114, s0, v[132:133]
	v_or_b32_e32 v98, 48, v128
	v_ashrrev_i32_e32 v99, 31, v98
	v_lshl_add_u64 v[100:101], v[100:101], 0, v[134:135]
	v_lshl_add_u64 v[102:103], v[98:99], 2, s[88:89]
	s_nop 1
	v_mov_b32_e32 v96, v237
	v_pk_mul_f32 v[94:95], v[94:95], v[96:97] op_sel_hi:[1,0]
	v_pk_mul_f32 v[92:93], v[92:93], v[96:97] op_sel_hi:[1,0]
	v_pk_mul_f32 v[90:91], v[90:91], v[96:97] op_sel_hi:[1,0]
	v_pk_mul_f32 v[88:89], v[88:89], v[96:97] op_sel_hi:[1,0]
	v_pk_mul_f32 v[82:83], v[82:83], v[96:97] op_sel_hi:[1,0]
	v_pk_mul_f32 v[80:81], v[80:81], v[96:97] op_sel_hi:[1,0]
	v_pk_mul_f32 v[104:105], v[74:75], v[96:97] op_sel_hi:[1,0]
	v_pk_mul_f32 v[96:97], v[72:73], v[96:97] op_sel_hi:[1,0]
	v_cvt_pk_bf16_f32 v72, v92, v93
	v_cvt_pk_bf16_f32 v73, v94, v95
	v_cvt_pk_bf16_f32 v74, v88, v89
	v_cvt_pk_bf16_f32 v75, v90, v91
	global_store_dwordx4 v[100:101], v[72:75], off
	s_nop 1
	v_cvt_pk_bf16_f32 v72, v80, v81
	v_cvt_pk_bf16_f32 v73, v82, v83
	v_cvt_pk_bf16_f32 v74, v96, v97
	v_cvt_pk_bf16_f32 v75, v104, v105
	global_store_dwordx4 v[100:101], v[72:75], off offset:256
	s_nop 1
	s_nop 1
	v_mov_b32_e32 v72, v238
	v_pk_mul_f32 v[80:81], v[86:87], v[72:73] op_sel_hi:[1,0]
	v_mad_i64_i32 v[74:75], s[4:5], v98, s0, v[132:133]
	v_lshl_add_u64 v[74:75], v[74:75], 0, v[134:135]
	v_pk_mul_f32 v[82:83], v[84:85], v[72:73] op_sel_hi:[1,0]
	v_pk_mul_f32 v[78:79], v[78:79], v[72:73] op_sel_hi:[1,0]
	v_pk_mul_f32 v[76:77], v[76:77], v[72:73] op_sel_hi:[1,0]
	v_pk_mul_f32 v[70:71], v[70:71], v[72:73] op_sel_hi:[1,0]
	v_pk_mul_f32 v[68:69], v[68:69], v[72:73] op_sel_hi:[1,0]
	v_pk_mul_f32 v[84:85], v[66:67], v[72:73] op_sel_hi:[1,0]
	v_pk_mul_f32 v[72:73], v[64:65], v[72:73] op_sel_hi:[1,0]
	v_cvt_pk_bf16_f32 v64, v82, v83
	v_cvt_pk_bf16_f32 v65, v80, v81
	v_cvt_pk_bf16_f32 v66, v76, v77
	v_cvt_pk_bf16_f32 v67, v78, v79
	global_store_dwordx4 v[74:75], v[64:67], off
	s_nop 1
	v_cvt_pk_bf16_f32 v64, v68, v69
	v_cvt_pk_bf16_f32 v65, v70, v71
	v_cvt_pk_bf16_f32 v66, v72, v73
	v_cvt_pk_bf16_f32 v67, v84, v85
	global_store_dwordx4 v[74:75], v[64:67], off offset:256
	s_nop 1
	s_nop 0
	v_add_u32_e32 v65, 0x80, v128
	v_mad_i64_i32 v[66:67], s[4:5], v65, s0, v[132:133]
	v_lshl_add_u64 v[66:67], v[66:67], 0, v[134:135]
	s_nop 1
	v_mov_b32_e32 v64, v239
	v_pk_mul_f32 v[62:63], v[62:63], v[64:65] op_sel_hi:[1,0]
	v_pk_mul_f32 v[60:61], v[60:61], v[64:65] op_sel_hi:[1,0]
	v_pk_mul_f32 v[58:59], v[58:59], v[64:65] op_sel_hi:[1,0]
	v_pk_mul_f32 v[56:57], v[56:57], v[64:65] op_sel_hi:[1,0]
	v_pk_mul_f32 v[54:55], v[54:55], v[64:65] op_sel_hi:[1,0]
	v_pk_mul_f32 v[52:53], v[52:53], v[64:65] op_sel_hi:[1,0]
	v_pk_mul_f32 v[68:69], v[50:51], v[64:65] op_sel_hi:[1,0]
	v_pk_mul_f32 v[64:65], v[48:49], v[64:65] op_sel_hi:[1,0]
	v_cvt_pk_bf16_f32 v48, v60, v61
	v_cvt_pk_bf16_f32 v49, v62, v63
	v_cvt_pk_bf16_f32 v50, v56, v57
	v_cvt_pk_bf16_f32 v51, v58, v59
	global_store_dwordx4 v[66:67], v[48:51], off
	s_nop 1
	v_cvt_pk_bf16_f32 v48, v52, v53
	v_cvt_pk_bf16_f32 v49, v54, v55
	v_cvt_pk_bf16_f32 v50, v64, v65
	v_cvt_pk_bf16_f32 v51, v68, v69
	global_store_dwordx4 v[66:67], v[48:51], off offset:256
	s_nop 1
	s_nop 0
	v_add_u32_e32 v49, 0x90, v128
	v_mad_i64_i32 v[50:51], s[4:5], v49, s0, v[132:133]
	v_lshl_add_u64 v[50:51], v[50:51], 0, v[134:135]
	s_nop 1
	v_mov_b32_e32 v48, v240
	v_pk_mul_f32 v[46:47], v[46:47], v[48:49] op_sel_hi:[1,0]
	v_pk_mul_f32 v[44:45], v[44:45], v[48:49] op_sel_hi:[1,0]
	v_pk_mul_f32 v[42:43], v[42:43], v[48:49] op_sel_hi:[1,0]
	v_pk_mul_f32 v[40:41], v[40:41], v[48:49] op_sel_hi:[1,0]
	v_pk_mul_f32 v[38:39], v[38:39], v[48:49] op_sel_hi:[1,0]
	v_pk_mul_f32 v[36:37], v[36:37], v[48:49] op_sel_hi:[1,0]
	v_pk_mul_f32 v[52:53], v[34:35], v[48:49] op_sel_hi:[1,0]
	v_pk_mul_f32 v[48:49], v[32:33], v[48:49] op_sel_hi:[1,0]
	v_cvt_pk_bf16_f32 v32, v44, v45
	v_cvt_pk_bf16_f32 v33, v46, v47
	v_cvt_pk_bf16_f32 v34, v40, v41
	v_cvt_pk_bf16_f32 v35, v42, v43
	global_store_dwordx4 v[50:51], v[32:35], off
	s_nop 1
	v_cvt_pk_bf16_f32 v32, v36, v37
	v_cvt_pk_bf16_f32 v33, v38, v39
	v_cvt_pk_bf16_f32 v34, v48, v49
	v_cvt_pk_bf16_f32 v35, v52, v53
	global_store_dwordx4 v[50:51], v[32:35], off offset:256
	s_nop 1
	s_nop 0
	v_add_u32_e32 v33, 0xa0, v128
	v_mad_i64_i32 v[34:35], s[4:5], v33, s0, v[132:133]
	v_lshl_add_u64 v[34:35], v[34:35], 0, v[134:135]
	s_nop 1
	v_mov_b32_e32 v32, v241
	v_pk_mul_f32 v[30:31], v[30:31], v[32:33] op_sel_hi:[1,0]
	v_pk_mul_f32 v[28:29], v[28:29], v[32:33] op_sel_hi:[1,0]
	v_pk_mul_f32 v[26:27], v[26:27], v[32:33] op_sel_hi:[1,0]
	v_pk_mul_f32 v[24:25], v[24:25], v[32:33] op_sel_hi:[1,0]
	v_pk_mul_f32 v[22:23], v[22:23], v[32:33] op_sel_hi:[1,0]
	v_pk_mul_f32 v[20:21], v[20:21], v[32:33] op_sel_hi:[1,0]
	v_pk_mul_f32 v[36:37], v[18:19], v[32:33] op_sel_hi:[1,0]
	v_pk_mul_f32 v[32:33], v[16:17], v[32:33] op_sel_hi:[1,0]
	v_cvt_pk_bf16_f32 v16, v28, v29
	v_cvt_pk_bf16_f32 v17, v30, v31
	v_cvt_pk_bf16_f32 v18, v24, v25
	v_cvt_pk_bf16_f32 v19, v26, v27
	global_store_dwordx4 v[34:35], v[16:19], off
	s_nop 1
	v_cvt_pk_bf16_f32 v16, v20, v21
	v_cvt_pk_bf16_f32 v17, v22, v23
	v_cvt_pk_bf16_f32 v18, v32, v33
	v_cvt_pk_bf16_f32 v19, v36, v37
	global_store_dwordx4 v[34:35], v[16:19], off offset:256
	s_nop 1
	s_nop 0
	v_add_u32_e32 v17, 0xb0, v128
	v_mad_i64_i32 v[18:19], s[0:1], v17, s0, v[132:133]
	v_lshl_add_u64 v[18:19], v[18:19], 0, v[134:135]
	v_readlane_b32 s0, v235, 41
	v_readlane_b32 s1, v235, 42
	s_and_b64 vcc, exec, s[0:1]
	s_nop 1
	v_mov_b32_e32 v16, v242
	v_pk_mul_f32 v[14:15], v[14:15], v[16:17] op_sel_hi:[1,0]
	v_pk_mul_f32 v[12:13], v[12:13], v[16:17] op_sel_hi:[1,0]
	v_pk_mul_f32 v[10:11], v[10:11], v[16:17] op_sel_hi:[1,0]
	v_pk_mul_f32 v[8:9], v[8:9], v[16:17] op_sel_hi:[1,0]
	v_pk_mul_f32 v[6:7], v[6:7], v[16:17] op_sel_hi:[1,0]
	v_pk_mul_f32 v[4:5], v[4:5], v[16:17] op_sel_hi:[1,0]
	v_pk_mul_f32 v[20:21], v[2:3], v[16:17] op_sel_hi:[1,0]
	v_pk_mul_f32 v[16:17], v[0:1], v[16:17] op_sel_hi:[1,0]
	v_cvt_pk_bf16_f32 v0, v12, v13
	v_cvt_pk_bf16_f32 v1, v14, v15
	v_cvt_pk_bf16_f32 v2, v8, v9
	v_cvt_pk_bf16_f32 v3, v10, v11
	global_store_dwordx4 v[18:19], v[0:3], off
	s_nop 1
	v_cvt_pk_bf16_f32 v0, v4, v5
	v_cvt_pk_bf16_f32 v1, v6, v7
	v_cvt_pk_bf16_f32 v2, v16, v17
	v_cvt_pk_bf16_f32 v3, v20, v21
	global_store_dwordx4 v[18:19], v[0:3], off offset:256
	s_waitcnt vmcnt(0)
	s_barrier
	s_waitcnt vmcnt(0)
	s_barrier
	s_cbranch_vccnz .LBB0_228
	v_mbcnt_lo_u32_b32 v0, -1, 0
	v_mbcnt_hi_u32_b32 v0, -1, v0
	s_nop 0
	v_cmp_eq_u32_e32 vcc, 0, v0
	s_and_saveexec_b64 s[0:1], vcc
	s_cbranch_execz .LBB0_227
	s_mov_b64 s[6:7], exec
	buffer_wbl2 sc1
	s_waitcnt vmcnt(0)
	s_waitcnt vmcnt(0)
	v_mbcnt_lo_u32_b32 v0, s6, 0
	s_add_u32 s4, s78, 0x3700
	v_mbcnt_hi_u32_b32 v0, s7, v0
	s_addc_u32 s5, s79, 0
	v_cmp_eq_u32_e32 vcc, 0, v0
	s_and_saveexec_b64 s[8:9], vcc
	s_cbranch_execz .LBB0_217
	s_bcnt1_i32_b64 s6, s[6:7]
	v_mov_b32_e32 v0, 0
	v_mov_b32_e32 v1, s6
	global_atomic_add v0, v1, s[4:5]

.LBB0_856:
	v_lshl_add_u32 v148, s19, 8, v154
	v_lshl_add_u32 v144, s18, 8, v152
	v_ashrrev_i32_e32 v149, 31, v148
	v_mov_b64_e32 v[146:147], s[52:53]
	v_ashrrev_i32_e32 v145, 31, v144
	v_mad_i64_i32 v[150:151], s[18:19], v144, s39, v[146:147]
	v_lshlrev_b64 v[148:149], 1, v[148:149]
	v_lshl_add_u64 v[158:159], v[150:151], 0, v[148:149]
	v_lshl_add_u64 v[150:151], v[144:145], 2, s[88:89]
	global_load_dword v160, v[150:151], off
	global_load_dword v236, v[150:151], off offset:64
	global_load_dword v237, v[150:151], off offset:128
	global_load_dword v238, v[150:151], off offset:192
	global_load_dword v239, v[150:151], off offset:512
	global_load_dword v240, v[150:151], off offset:576
	global_load_dword v241, v[150:151], off offset:640
	global_load_dword v242, v[150:151], off offset:704
	s_andn2_b64 vcc, exec, s[8:9]
	s_waitcnt vmcnt(0)
	v_pk_mul_f32 v[126:127], v[126:127], v[160:161] op_sel_hi:[1,0]
	v_pk_mul_f32 v[124:125], v[124:125], v[160:161] op_sel_hi:[1,0]
	v_pk_mul_f32 v[162:163], v[122:123], v[160:161] op_sel_hi:[1,0]
	v_pk_mul_f32 v[122:123], v[120:121], v[160:161] op_sel_hi:[1,0]
	v_cvt_pk_bf16_f32 v120, v124, v125
	v_cvt_pk_bf16_f32 v121, v126, v127
	v_pk_mul_f32 v[116:117], v[116:117], v[160:161] op_sel_hi:[1,0]
	v_cvt_pk_bf16_f32 v122, v122, v123
	v_cvt_pk_bf16_f32 v123, v162, v163
	global_store_dwordx4 v[158:159], v[120:123], off
	v_pk_mul_f32 v[118:119], v[118:119], v[160:161] op_sel_hi:[1,0]
	s_nop 0
	v_pk_mul_f32 v[120:121], v[114:115], v[160:161] op_sel_hi:[1,0]
	v_pk_mul_f32 v[114:115], v[112:113], v[160:161] op_sel_hi:[1,0]
	v_cvt_pk_bf16_f32 v112, v116, v117
	v_cvt_pk_bf16_f32 v113, v118, v119
	s_nop 0
	v_cvt_pk_bf16_f32 v114, v114, v115
	v_cvt_pk_bf16_f32 v115, v120, v121
	global_store_dwordx4 v[158:159], v[112:115], off offset:256
	s_nop 1
	v_or_b32_e32 v112, 16, v144
	v_ashrrev_i32_e32 v113, 31, v112
	v_mad_i64_i32 v[114:115], s[18:19], v112, s39, v[146:147]
	v_lshl_add_u64 v[112:113], v[112:113], 2, s[88:89]
	s_nop 1
	v_lshl_add_u64 v[114:115], v[114:115], 0, v[148:149]
	s_nop 1
	v_mov_b32_e32 v112, v236
	v_pk_mul_f32 v[110:111], v[110:111], v[112:113] op_sel_hi:[1,0]
	v_pk_mul_f32 v[108:109], v[108:109], v[112:113] op_sel_hi:[1,0]
	v_pk_mul_f32 v[116:117], v[106:107], v[112:113] op_sel_hi:[1,0]
	v_pk_mul_f32 v[106:107], v[104:105], v[112:113] op_sel_hi:[1,0]
	v_cvt_pk_bf16_f32 v104, v108, v109
	v_cvt_pk_bf16_f32 v105, v110, v111
	v_pk_mul_f32 v[100:101], v[100:101], v[112:113] op_sel_hi:[1,0]
	v_cvt_pk_bf16_f32 v106, v106, v107
	v_cvt_pk_bf16_f32 v107, v116, v117
	global_store_dwordx4 v[114:115], v[104:107], off
	v_pk_mul_f32 v[102:103], v[102:103], v[112:113] op_sel_hi:[1,0]
	s_nop 0
	v_pk_mul_f32 v[104:105], v[98:99], v[112:113] op_sel_hi:[1,0]
	v_pk_mul_f32 v[98:99], v[96:97], v[112:113] op_sel_hi:[1,0]
	v_cvt_pk_bf16_f32 v96, v100, v101
	v_cvt_pk_bf16_f32 v97, v102, v103
	s_nop 0
	v_cvt_pk_bf16_f32 v98, v98, v99
	v_cvt_pk_bf16_f32 v99, v104, v105
	global_store_dwordx4 v[114:115], v[96:99], off offset:256
	s_nop 1
	v_or_b32_e32 v96, 32, v144
	v_ashrrev_i32_e32 v97, 31, v96
	v_mad_i64_i32 v[98:99], s[18:19], v96, s39, v[146:147]
	v_lshl_add_u64 v[96:97], v[96:97], 2, s[88:89]
	s_nop 1
	v_lshl_add_u64 v[98:99], v[98:99], 0, v[148:149]
	s_nop 1
	v_mov_b32_e32 v96, v237
	v_pk_mul_f32 v[94:95], v[94:95], v[96:97] op_sel_hi:[1,0]
	v_pk_mul_f32 v[92:93], v[92:93], v[96:97] op_sel_hi:[1,0]
	v_pk_mul_f32 v[100:101], v[90:91], v[96:97] op_sel_hi:[1,0]
	v_pk_mul_f32 v[90:91], v[88:89], v[96:97] op_sel_hi:[1,0]
	v_cvt_pk_bf16_f32 v88, v92, v93
	v_cvt_pk_bf16_f32 v89, v94, v95
	v_pk_mul_f32 v[84:85], v[84:85], v[96:97] op_sel_hi:[1,0]
	v_cvt_pk_bf16_f32 v90, v90, v91
	v_cvt_pk_bf16_f32 v91, v100, v101
	global_store_dwordx4 v[98:99], v[88:91], off
	v_pk_mul_f32 v[86:87], v[86:87], v[96:97] op_sel_hi:[1,0]
	s_nop 0
	v_pk_mul_f32 v[88:89], v[82:83], v[96:97] op_sel_hi:[1,0]
	v_pk_mul_f32 v[82:83], v[80:81], v[96:97] op_sel_hi:[1,0]
	v_cvt_pk_bf16_f32 v80, v84, v85
	v_cvt_pk_bf16_f32 v81, v86, v87
	s_nop 0
	v_cvt_pk_bf16_f32 v82, v82, v83
	v_cvt_pk_bf16_f32 v83, v88, v89
	global_store_dwordx4 v[98:99], v[80:83], off offset:256
	s_nop 1
	v_or_b32_e32 v80, 48, v144
	v_ashrrev_i32_e32 v81, 31, v80
	v_mad_i64_i32 v[82:83], s[18:19], v80, s39, v[146:147]
	v_lshl_add_u64 v[80:81], v[80:81], 2, s[88:89]
	s_nop 1
	v_lshl_add_u64 v[82:83], v[82:83], 0, v[148:149]
	s_nop 1
	v_mov_b32_e32 v80, v238
	v_pk_mul_f32 v[78:79], v[78:79], v[80:81] op_sel_hi:[1,0]
	v_pk_mul_f32 v[76:77], v[76:77], v[80:81] op_sel_hi:[1,0]
	v_pk_mul_f32 v[84:85], v[74:75], v[80:81] op_sel_hi:[1,0]
	v_pk_mul_f32 v[74:75], v[72:73], v[80:81] op_sel_hi:[1,0]
	v_cvt_pk_bf16_f32 v72, v76, v77
	v_cvt_pk_bf16_f32 v73, v78, v79
	v_pk_mul_f32 v[70:71], v[70:71], v[80:81] op_sel_hi:[1,0]
	v_cvt_pk_bf16_f32 v74, v74, v75
	v_cvt_pk_bf16_f32 v75, v84, v85
	global_store_dwordx4 v[82:83], v[72:75], off
	v_pk_mul_f32 v[68:69], v[68:69], v[80:81] op_sel_hi:[1,0]
	s_nop 0
	v_pk_mul_f32 v[72:73], v[66:67], v[80:81] op_sel_hi:[1,0]
	v_pk_mul_f32 v[66:67], v[64:65], v[80:81] op_sel_hi:[1,0]
	v_cvt_pk_bf16_f32 v64, v68, v69
	v_cvt_pk_bf16_f32 v65, v70, v71
	s_nop 0
	v_cvt_pk_bf16_f32 v66, v66, v67
	v_cvt_pk_bf16_f32 v67, v72, v73
	global_store_dwordx4 v[82:83], v[64:67], off offset:256
	s_nop 1
	s_nop 1
	v_mov_b32_e32 v66, v239
	v_pk_mul_f32 v[62:63], v[62:63], v[66:67] op_sel_hi:[1,0]
	v_add_u32_e32 v64, 0x80, v144
	v_mad_i64_i32 v[64:65], s[18:19], v64, s39, v[146:147]
	v_lshl_add_u64 v[64:65], v[64:65], 0, v[148:149]
	v_pk_mul_f32 v[60:61], v[60:61], v[66:67] op_sel_hi:[1,0]
	v_pk_mul_f32 v[68:69], v[58:59], v[66:67] op_sel_hi:[1,0]
	v_pk_mul_f32 v[58:59], v[56:57], v[66:67] op_sel_hi:[1,0]
	v_cvt_pk_bf16_f32 v56, v60, v61
	v_cvt_pk_bf16_f32 v57, v62, v63
	v_pk_mul_f32 v[54:55], v[54:55], v[66:67] op_sel_hi:[1,0]
	v_cvt_pk_bf16_f32 v58, v58, v59
	v_cvt_pk_bf16_f32 v59, v68, v69
	global_store_dwordx4 v[64:65], v[56:59], off
	v_pk_mul_f32 v[52:53], v[52:53], v[66:67] op_sel_hi:[1,0]
	s_nop 0
	v_pk_mul_f32 v[56:57], v[50:51], v[66:67] op_sel_hi:[1,0]
	v_pk_mul_f32 v[50:51], v[48:49], v[66:67] op_sel_hi:[1,0]
	v_cvt_pk_bf16_f32 v48, v52, v53
	v_cvt_pk_bf16_f32 v49, v54, v55
	s_nop 0
	v_cvt_pk_bf16_f32 v50, v50, v51
	v_cvt_pk_bf16_f32 v51, v56, v57
	global_store_dwordx4 v[64:65], v[48:51], off offset:256
	s_nop 1
	s_nop 1
	v_mov_b32_e32 v50, v240
	v_pk_mul_f32 v[46:47], v[46:47], v[50:51] op_sel_hi:[1,0]
	v_add_u32_e32 v48, 0x90, v144
	v_mad_i64_i32 v[48:49], s[18:19], v48, s39, v[146:147]
	v_lshl_add_u64 v[48:49], v[48:49], 0, v[148:149]
	v_pk_mul_f32 v[44:45], v[44:45], v[50:51] op_sel_hi:[1,0]
	v_pk_mul_f32 v[52:53], v[42:43], v[50:51] op_sel_hi:[1,0]
	v_pk_mul_f32 v[42:43], v[40:41], v[50:51] op_sel_hi:[1,0]
	v_cvt_pk_bf16_f32 v40, v44, v45
	v_cvt_pk_bf16_f32 v41, v46, v47
	v_pk_mul_f32 v[38:39], v[38:39], v[50:51] op_sel_hi:[1,0]
	v_cvt_pk_bf16_f32 v42, v42, v43
	v_cvt_pk_bf16_f32 v43, v52, v53
	global_store_dwordx4 v[48:49], v[40:43], off
	v_pk_mul_f32 v[36:37], v[36:37], v[50:51] op_sel_hi:[1,0]
	s_nop 0
	v_pk_mul_f32 v[40:41], v[34:35], v[50:51] op_sel_hi:[1,0]
	v_pk_mul_f32 v[34:35], v[32:33], v[50:51] op_sel_hi:[1,0]
	v_cvt_pk_bf16_f32 v32, v36, v37
	v_cvt_pk_bf16_f32 v33, v38, v39
	s_nop 0
	v_cvt_pk_bf16_f32 v34, v34, v35
	v_cvt_pk_bf16_f32 v35, v40, v41
	global_store_dwordx4 v[48:49], v[32:35], off offset:256
	s_nop 1
	s_nop 1
	v_mov_b32_e32 v34, v241
	v_pk_mul_f32 v[30:31], v[30:31], v[34:35] op_sel_hi:[1,0]
	v_add_u32_e32 v32, 0xa0, v144
	v_mad_i64_i32 v[32:33], s[18:19], v32, s39, v[146:147]
	v_lshl_add_u64 v[32:33], v[32:33], 0, v[148:149]
	v_pk_mul_f32 v[28:29], v[28:29], v[34:35] op_sel_hi:[1,0]
	v_pk_mul_f32 v[36:37], v[26:27], v[34:35] op_sel_hi:[1,0]
	v_pk_mul_f32 v[26:27], v[24:25], v[34:35] op_sel_hi:[1,0]
	v_cvt_pk_bf16_f32 v24, v28, v29
	v_cvt_pk_bf16_f32 v25, v30, v31
	v_pk_mul_f32 v[22:23], v[22:23], v[34:35] op_sel_hi:[1,0]
	v_cvt_pk_bf16_f32 v26, v26, v27
	v_cvt_pk_bf16_f32 v27, v36, v37
	global_store_dwordx4 v[32:33], v[24:27], off
	v_pk_mul_f32 v[20:21], v[20:21], v[34:35] op_sel_hi:[1,0]
	s_nop 0
	v_pk_mul_f32 v[24:25], v[18:19], v[34:35] op_sel_hi:[1,0]
	v_pk_mul_f32 v[18:19], v[16:17], v[34:35] op_sel_hi:[1,0]
	v_cvt_pk_bf16_f32 v16, v20, v21
	v_cvt_pk_bf16_f32 v17, v22, v23
	s_nop 0
	v_cvt_pk_bf16_f32 v18, v18, v19
	v_cvt_pk_bf16_f32 v19, v24, v25
	global_store_dwordx4 v[32:33], v[16:19], off offset:256
	s_nop 1
	s_nop 1
	v_mov_b32_e32 v18, v242
	v_pk_mul_f32 v[14:15], v[14:15], v[18:19] op_sel_hi:[1,0]
	v_add_u32_e32 v16, 0xb0, v144
	v_mad_i64_i32 v[16:17], s[18:19], v16, s39, v[146:147]
	v_lshl_add_u64 v[16:17], v[16:17], 0, v[148:149]
	v_pk_mul_f32 v[12:13], v[12:13], v[18:19] op_sel_hi:[1,0]
	v_pk_mul_f32 v[20:21], v[10:11], v[18:19] op_sel_hi:[1,0]
	v_pk_mul_f32 v[10:11], v[8:9], v[18:19] op_sel_hi:[1,0]
	v_cvt_pk_bf16_f32 v8, v12, v13
	v_cvt_pk_bf16_f32 v9, v14, v15
	s_mov_b64 s[18:19], -1
	v_cvt_pk_bf16_f32 v10, v10, v11
	v_cvt_pk_bf16_f32 v11, v20, v21
	global_store_dwordx4 v[16:17], v[8:11], off
	v_pk_mul_f32 v[6:7], v[6:7], v[18:19] op_sel_hi:[1,0]
	v_pk_mul_f32 v[4:5], v[4:5], v[18:19] op_sel_hi:[1,0]
	v_pk_mul_f32 v[8:9], v[2:3], v[18:19] op_sel_hi:[1,0]
	v_pk_mul_f32 v[2:3], v[0:1], v[18:19] op_sel_hi:[1,0]
	v_cvt_pk_bf16_f32 v0, v4, v5
	v_cvt_pk_bf16_f32 v1, v6, v7
	s_nop 0
	v_cvt_pk_bf16_f32 v2, v2, v3
	v_cvt_pk_bf16_f32 v3, v8, v9
	global_store_dwordx4 v[16:17], v[0:3], off offset:256
	s_cbranch_vccnz .LBB0_847
	s_andn2_b64 vcc, exec, s[0:1]
	s_cbranch_vccnz .LBB0_846
	s_barrier
	s_branch .LBB0_846

.LBB0_922:
	v_ashrrev_i32_e32 v128, 1, v140
	v_and_b32_e32 v129, -8, v128
	v_lshl_add_u32 v128, s0, 8, v141
	s_lshl_b32 s0, s4, 8
	v_readlane_b32 s1, v235, 37
	s_or_b32 s0, s1, s0
	v_add_u32_e32 v132, s0, v129
	v_ashrrev_i32_e32 v133, 31, v132
	s_movk_i32 s0, 0x1040
	v_mov_b64_e32 v[130:131], s[52:53]
	v_ashrrev_i32_e32 v129, 31, v128
	v_mad_i64_i32 v[134:135], s[4:5], v128, s0, v[130:131]
	v_lshlrev_b64 v[132:133], 1, v[132:133]
	v_lshl_add_u64 v[136:137], v[134:135], 0, v[132:133]
	v_lshl_add_u64 v[134:135], v[128:129], 2, s[88:89]
	global_load_dword v138, v[134:135], off
	global_load_dword v236, v[134:135], off offset:64
	global_load_dword v237, v[134:135], off offset:128
	global_load_dword v238, v[134:135], off offset:192
	global_load_dword v239, v[134:135], off offset:512
	global_load_dword v240, v[134:135], off offset:576
	global_load_dword v241, v[134:135], off offset:640
	global_load_dword v242, v[134:135], off offset:704
	s_waitcnt vmcnt(0)
	v_pk_mul_f32 v[126:127], v[126:127], v[138:139] op_sel_hi:[1,0]
	v_pk_mul_f32 v[124:125], v[124:125], v[138:139] op_sel_hi:[1,0]
	v_pk_mul_f32 v[140:141], v[122:123], v[138:139] op_sel_hi:[1,0]
	v_pk_mul_f32 v[122:123], v[120:121], v[138:139] op_sel_hi:[1,0]
	v_cvt_pk_bf16_f32 v120, v124, v125
	v_cvt_pk_bf16_f32 v121, v126, v127
	v_pk_mul_f32 v[116:117], v[116:117], v[138:139] op_sel_hi:[1,0]
	v_cvt_pk_bf16_f32 v122, v122, v123
	v_cvt_pk_bf16_f32 v123, v140, v141
	global_store_dwordx4 v[136:137], v[120:123], off
	v_pk_mul_f32 v[118:119], v[118:119], v[138:139] op_sel_hi:[1,0]
	s_nop 0
	v_pk_mul_f32 v[120:121], v[114:115], v[138:139] op_sel_hi:[1,0]
	v_pk_mul_f32 v[114:115], v[112:113], v[138:139] op_sel_hi:[1,0]
	v_cvt_pk_bf16_f32 v112, v116, v117
	v_cvt_pk_bf16_f32 v113, v118, v119
	s_nop 0
	v_cvt_pk_bf16_f32 v114, v114, v115
	v_cvt_pk_bf16_f32 v115, v120, v121
	global_store_dwordx4 v[136:137], v[112:115], off offset:256
	s_nop 1
	v_or_b32_e32 v112, 16, v128
	v_ashrrev_i32_e32 v113, 31, v112
	v_mad_i64_i32 v[114:115], s[4:5], v112, s0, v[130:131]
	v_lshl_add_u64 v[112:113], v[112:113], 2, s[88:89]
	s_nop 1
	v_lshl_add_u64 v[114:115], v[114:115], 0, v[132:133]
	s_nop 1
	v_mov_b32_e32 v112, v236
	v_pk_mul_f32 v[110:111], v[110:111], v[112:113] op_sel_hi:[1,0]
	v_pk_mul_f32 v[108:109], v[108:109], v[112:113] op_sel_hi:[1,0]
	v_pk_mul_f32 v[116:117], v[106:107], v[112:113] op_sel_hi:[1,0]
	v_pk_mul_f32 v[106:107], v[104:105], v[112:113] op_sel_hi:[1,0]
	v_cvt_pk_bf16_f32 v104, v108, v109
	v_cvt_pk_bf16_f32 v105, v110, v111
	v_pk_mul_f32 v[100:101], v[100:101], v[112:113] op_sel_hi:[1,0]
	v_cvt_pk_bf16_f32 v106, v106, v107
	v_cvt_pk_bf16_f32 v107, v116, v117
	global_store_dwordx4 v[114:115], v[104:107], off
	v_pk_mul_f32 v[102:103], v[102:103], v[112:113] op_sel_hi:[1,0]
	s_nop 0
	v_pk_mul_f32 v[104:105], v[98:99], v[112:113] op_sel_hi:[1,0]
	v_pk_mul_f32 v[98:99], v[96:97], v[112:113] op_sel_hi:[1,0]
	v_cvt_pk_bf16_f32 v96, v100, v101
	v_cvt_pk_bf16_f32 v97, v102, v103
	s_nop 0
	v_cvt_pk_bf16_f32 v98, v98, v99
	v_cvt_pk_bf16_f32 v99, v104, v105
	global_store_dwordx4 v[114:115], v[96:99], off offset:256
	s_nop 1
	v_or_b32_e32 v96, 32, v128
	v_ashrrev_i32_e32 v97, 31, v96
	v_mad_i64_i32 v[98:99], s[4:5], v96, s0, v[130:131]
	v_lshl_add_u64 v[96:97], v[96:97], 2, s[88:89]
	s_nop 1
	v_lshl_add_u64 v[98:99], v[98:99], 0, v[132:133]
	s_nop 1
	v_mov_b32_e32 v96, v237
	v_pk_mul_f32 v[94:95], v[94:95], v[96:97] op_sel_hi:[1,0]
	v_pk_mul_f32 v[92:93], v[92:93], v[96:97] op_sel_hi:[1,0]
	v_pk_mul_f32 v[100:101], v[90:91], v[96:97] op_sel_hi:[1,0]
	v_pk_mul_f32 v[90:91], v[88:89], v[96:97] op_sel_hi:[1,0]
	v_cvt_pk_bf16_f32 v88, v92, v93
	v_cvt_pk_bf16_f32 v89, v94, v95
	v_pk_mul_f32 v[84:85], v[84:85], v[96:97] op_sel_hi:[1,0]
	v_cvt_pk_bf16_f32 v90, v90, v91
	v_cvt_pk_bf16_f32 v91, v100, v101
	global_store_dwordx4 v[98:99], v[88:91], off
	v_pk_mul_f32 v[86:87], v[86:87], v[96:97] op_sel_hi:[1,0]
	s_nop 0
	v_pk_mul_f32 v[88:89], v[82:83], v[96:97] op_sel_hi:[1,0]
	v_pk_mul_f32 v[82:83], v[80:81], v[96:97] op_sel_hi:[1,0]
	v_cvt_pk_bf16_f32 v80, v84, v85
	v_cvt_pk_bf16_f32 v81, v86, v87
	s_nop 0
	v_cvt_pk_bf16_f32 v82, v82, v83
	v_cvt_pk_bf16_f32 v83, v88, v89
	global_store_dwordx4 v[98:99], v[80:83], off offset:256
	s_nop 1
	v_or_b32_e32 v80, 48, v128
	v_ashrrev_i32_e32 v81, 31, v80
	v_mad_i64_i32 v[82:83], s[4:5], v80, s0, v[130:131]
	v_lshl_add_u64 v[80:81], v[80:81], 2, s[88:89]
	s_nop 1
	v_lshl_add_u64 v[82:83], v[82:83], 0, v[132:133]
	s_nop 1
	v_mov_b32_e32 v80, v238
	v_pk_mul_f32 v[78:79], v[78:79], v[80:81] op_sel_hi:[1,0]
	v_pk_mul_f32 v[76:77], v[76:77], v[80:81] op_sel_hi:[1,0]
	v_pk_mul_f32 v[84:85], v[74:75], v[80:81] op_sel_hi:[1,0]
	v_pk_mul_f32 v[74:75], v[72:73], v[80:81] op_sel_hi:[1,0]
	v_cvt_pk_bf16_f32 v72, v76, v77
	v_cvt_pk_bf16_f32 v73, v78, v79
	v_pk_mul_f32 v[70:71], v[70:71], v[80:81] op_sel_hi:[1,0]
	v_cvt_pk_bf16_f32 v74, v74, v75
	v_cvt_pk_bf16_f32 v75, v84, v85
	global_store_dwordx4 v[82:83], v[72:75], off
	v_pk_mul_f32 v[68:69], v[68:69], v[80:81] op_sel_hi:[1,0]
	s_nop 0
	v_pk_mul_f32 v[72:73], v[66:67], v[80:81] op_sel_hi:[1,0]
	v_pk_mul_f32 v[66:67], v[64:65], v[80:81] op_sel_hi:[1,0]
	v_cvt_pk_bf16_f32 v64, v68, v69
	v_cvt_pk_bf16_f32 v65, v70, v71
	s_nop 0
	v_cvt_pk_bf16_f32 v66, v66, v67
	v_cvt_pk_bf16_f32 v67, v72, v73
	global_store_dwordx4 v[82:83], v[64:67], off offset:256
	s_nop 1
	s_nop 1
	v_mov_b32_e32 v66, v239
	v_pk_mul_f32 v[62:63], v[62:63], v[66:67] op_sel_hi:[1,0]
	v_add_u32_e32 v64, 0x80, v128
	v_mad_i64_i32 v[64:65], s[4:5], v64, s0, v[130:131]
	v_lshl_add_u64 v[64:65], v[64:65], 0, v[132:133]
	v_pk_mul_f32 v[60:61], v[60:61], v[66:67] op_sel_hi:[1,0]
	v_pk_mul_f32 v[68:69], v[58:59], v[66:67] op_sel_hi:[1,0]
	v_pk_mul_f32 v[58:59], v[56:57], v[66:67] op_sel_hi:[1,0]
	v_cvt_pk_bf16_f32 v56, v60, v61
	v_cvt_pk_bf16_f32 v57, v62, v63
	v_pk_mul_f32 v[54:55], v[54:55], v[66:67] op_sel_hi:[1,0]
	v_cvt_pk_bf16_f32 v58, v58, v59
	v_cvt_pk_bf16_f32 v59, v68, v69
	global_store_dwordx4 v[64:65], v[56:59], off
	v_pk_mul_f32 v[52:53], v[52:53], v[66:67] op_sel_hi:[1,0]
	s_nop 0
	v_pk_mul_f32 v[56:57], v[50:51], v[66:67] op_sel_hi:[1,0]
	v_pk_mul_f32 v[50:51], v[48:49], v[66:67] op_sel_hi:[1,0]
	v_cvt_pk_bf16_f32 v48, v52, v53
	v_cvt_pk_bf16_f32 v49, v54, v55
	s_nop 0
	v_cvt_pk_bf16_f32 v50, v50, v51
	v_cvt_pk_bf16_f32 v51, v56, v57
	global_store_dwordx4 v[64:65], v[48:51], off offset:256
	s_nop 1
	s_nop 1
	v_mov_b32_e32 v50, v240
	v_pk_mul_f32 v[46:47], v[46:47], v[50:51] op_sel_hi:[1,0]
	v_add_u32_e32 v48, 0x90, v128
	v_mad_i64_i32 v[48:49], s[4:5], v48, s0, v[130:131]
	v_lshl_add_u64 v[48:49], v[48:49], 0, v[132:133]
	v_pk_mul_f32 v[44:45], v[44:45], v[50:51] op_sel_hi:[1,0]
	v_pk_mul_f32 v[52:53], v[42:43], v[50:51] op_sel_hi:[1,0]
	v_pk_mul_f32 v[42:43], v[40:41], v[50:51] op_sel_hi:[1,0]
	v_cvt_pk_bf16_f32 v40, v44, v45
	v_cvt_pk_bf16_f32 v41, v46, v47
	v_pk_mul_f32 v[38:39], v[38:39], v[50:51] op_sel_hi:[1,0]
	v_cvt_pk_bf16_f32 v42, v42, v43
	v_cvt_pk_bf16_f32 v43, v52, v53
	global_store_dwordx4 v[48:49], v[40:43], off
	v_pk_mul_f32 v[36:37], v[36:37], v[50:51] op_sel_hi:[1,0]
	s_nop 0
	v_pk_mul_f32 v[40:41], v[34:35], v[50:51] op_sel_hi:[1,0]
	v_pk_mul_f32 v[34:35], v[32:33], v[50:51] op_sel_hi:[1,0]
	v_cvt_pk_bf16_f32 v32, v36, v37
	v_cvt_pk_bf16_f32 v33, v38, v39
	s_nop 0
	v_cvt_pk_bf16_f32 v34, v34, v35
	v_cvt_pk_bf16_f32 v35, v40, v41
	global_store_dwordx4 v[48:49], v[32:35], off offset:256
	s_nop 1
	s_nop 1
	v_mov_b32_e32 v34, v241
	v_pk_mul_f32 v[30:31], v[30:31], v[34:35] op_sel_hi:[1,0]
	v_add_u32_e32 v32, 0xa0, v128
	v_mad_i64_i32 v[32:33], s[4:5], v32, s0, v[130:131]
	v_lshl_add_u64 v[32:33], v[32:33], 0, v[132:133]
	v_pk_mul_f32 v[28:29], v[28:29], v[34:35] op_sel_hi:[1,0]
	v_pk_mul_f32 v[36:37], v[26:27], v[34:35] op_sel_hi:[1,0]
	v_pk_mul_f32 v[26:27], v[24:25], v[34:35] op_sel_hi:[1,0]
	v_cvt_pk_bf16_f32 v24, v28, v29
	v_cvt_pk_bf16_f32 v25, v30, v31
	v_pk_mul_f32 v[22:23], v[22:23], v[34:35] op_sel_hi:[1,0]
	v_cvt_pk_bf16_f32 v26, v26, v27
	v_cvt_pk_bf16_f32 v27, v36, v37
	global_store_dwordx4 v[32:33], v[24:27], off
	v_pk_mul_f32 v[20:21], v[20:21], v[34:35] op_sel_hi:[1,0]
	s_nop 0
	v_pk_mul_f32 v[24:25], v[18:19], v[34:35] op_sel_hi:[1,0]
	v_pk_mul_f32 v[18:19], v[16:17], v[34:35] op_sel_hi:[1,0]
	v_cvt_pk_bf16_f32 v16, v20, v21
	v_cvt_pk_bf16_f32 v17, v22, v23
	s_nop 0
	v_cvt_pk_bf16_f32 v18, v18, v19
	v_cvt_pk_bf16_f32 v19, v24, v25
	global_store_dwordx4 v[32:33], v[16:19], off offset:256
	s_nop 1
	s_nop 1
	v_mov_b32_e32 v18, v242
	v_pk_mul_f32 v[14:15], v[14:15], v[18:19] op_sel_hi:[1,0]
	v_add_u32_e32 v16, 0xb0, v128
	v_mad_i64_i32 v[16:17], s[0:1], v16, s0, v[130:131]
	v_lshl_add_u64 v[16:17], v[16:17], 0, v[132:133]
	v_pk_mul_f32 v[12:13], v[12:13], v[18:19] op_sel_hi:[1,0]
	v_pk_mul_f32 v[20:21], v[10:11], v[18:19] op_sel_hi:[1,0]
	v_pk_mul_f32 v[10:11], v[8:9], v[18:19] op_sel_hi:[1,0]
	v_cvt_pk_bf16_f32 v8, v12, v13
	v_cvt_pk_bf16_f32 v9, v14, v15
	v_pk_mul_f32 v[6:7], v[6:7], v[18:19] op_sel_hi:[1,0]
	v_cvt_pk_bf16_f32 v10, v10, v11
	v_cvt_pk_bf16_f32 v11, v20, v21
	global_store_dwordx4 v[16:17], v[8:11], off
	v_pk_mul_f32 v[4:5], v[4:5], v[18:19] op_sel_hi:[1,0]
	v_readlane_b32 s0, v235, 41
	v_pk_mul_f32 v[8:9], v[2:3], v[18:19] op_sel_hi:[1,0]
	v_pk_mul_f32 v[2:3], v[0:1], v[18:19] op_sel_hi:[1,0]
	v_cvt_pk_bf16_f32 v0, v4, v5
	v_cvt_pk_bf16_f32 v1, v6, v7
	v_readlane_b32 s1, v235, 42
	v_cvt_pk_bf16_f32 v2, v2, v3
	v_cvt_pk_bf16_f32 v3, v8, v9
	global_store_dwordx4 v[16:17], v[0:3], off offset:256
	s_waitcnt vmcnt(0)
	s_barrier
	s_waitcnt vmcnt(0)
	s_and_b64 vcc, exec, s[0:1]
	s_barrier
	s_cbranch_vccnz .LBB0_936
	v_mbcnt_lo_u32_b32 v0, -1, 0
	v_mbcnt_hi_u32_b32 v0, -1, v0
	s_nop 0
	v_cmp_eq_u32_e32 vcc, 0, v0
	s_and_saveexec_b64 s[0:1], vcc
	s_cbranch_execz .LBB0_935
	s_mov_b64 s[6:7], exec
	buffer_wbl2 sc1
	s_waitcnt vmcnt(0)
	s_waitcnt vmcnt(0)
	v_mbcnt_lo_u32_b32 v0, s6, 0
	s_add_u32 s4, s78, 0x3800
	v_mbcnt_hi_u32_b32 v0, s7, v0
	s_addc_u32 s5, s79, 0
	v_cmp_eq_u32_e32 vcc, 0, v0
	s_and_saveexec_b64 s[8:9], vcc
	s_cbranch_execz .LBB0_926
	s_bcnt1_i32_b64 s6, s[6:7]
	v_mov_b32_e32 v0, 0
	v_mov_b32_e32 v1, s6
	global_atomic_add v0, v1, s[4:5]

.LBB0_1565:
	v_lshl_add_u32 v148, s19, 8, v154
	v_lshl_add_u32 v144, s18, 8, v152
	v_ashrrev_i32_e32 v149, 31, v148
	v_mov_b64_e32 v[146:147], s[52:53]
	v_ashrrev_i32_e32 v145, 31, v144
	v_mad_i64_i32 v[150:151], s[18:19], v144, s39, v[146:147]
	v_lshlrev_b64 v[148:149], 1, v[148:149]
	v_lshl_add_u64 v[158:159], v[150:151], 0, v[148:149]
	v_lshl_add_u64 v[150:151], v[144:145], 2, s[88:89]
	global_load_dword v160, v[150:151], off
	global_load_dword v236, v[150:151], off offset:64
	global_load_dword v237, v[150:151], off offset:128
	global_load_dword v238, v[150:151], off offset:192
	global_load_dword v239, v[150:151], off offset:512
	global_load_dword v240, v[150:151], off offset:576
	global_load_dword v241, v[150:151], off offset:640
	global_load_dword v242, v[150:151], off offset:704
	s_andn2_b64 vcc, exec, s[16:17]
	s_waitcnt vmcnt(0)
	v_pk_mul_f32 v[126:127], v[126:127], v[160:161] op_sel_hi:[1,0]
	v_pk_mul_f32 v[124:125], v[124:125], v[160:161] op_sel_hi:[1,0]
	v_pk_mul_f32 v[162:163], v[122:123], v[160:161] op_sel_hi:[1,0]
	v_pk_mul_f32 v[122:123], v[120:121], v[160:161] op_sel_hi:[1,0]
	v_cvt_pk_bf16_f32 v120, v124, v125
	v_cvt_pk_bf16_f32 v121, v126, v127
	v_pk_mul_f32 v[116:117], v[116:117], v[160:161] op_sel_hi:[1,0]
	v_cvt_pk_bf16_f32 v122, v122, v123
	v_cvt_pk_bf16_f32 v123, v162, v163
	global_store_dwordx4 v[158:159], v[120:123], off
	v_pk_mul_f32 v[118:119], v[118:119], v[160:161] op_sel_hi:[1,0]
	s_nop 0
	v_pk_mul_f32 v[120:121], v[114:115], v[160:161] op_sel_hi:[1,0]
	v_pk_mul_f32 v[114:115], v[112:113], v[160:161] op_sel_hi:[1,0]
	v_cvt_pk_bf16_f32 v112, v116, v117
	v_cvt_pk_bf16_f32 v113, v118, v119
	s_nop 0
	v_cvt_pk_bf16_f32 v114, v114, v115
	v_cvt_pk_bf16_f32 v115, v120, v121
	global_store_dwordx4 v[158:159], v[112:115], off offset:256
	s_nop 1
	v_or_b32_e32 v112, 16, v144
	v_ashrrev_i32_e32 v113, 31, v112
	v_mad_i64_i32 v[114:115], s[18:19], v112, s39, v[146:147]
	v_lshl_add_u64 v[112:113], v[112:113], 2, s[88:89]
	s_nop 1
	v_lshl_add_u64 v[114:115], v[114:115], 0, v[148:149]
	s_nop 1
	v_mov_b32_e32 v112, v236
	v_pk_mul_f32 v[110:111], v[110:111], v[112:113] op_sel_hi:[1,0]
	v_pk_mul_f32 v[108:109], v[108:109], v[112:113] op_sel_hi:[1,0]
	v_pk_mul_f32 v[116:117], v[106:107], v[112:113] op_sel_hi:[1,0]
	v_pk_mul_f32 v[106:107], v[104:105], v[112:113] op_sel_hi:[1,0]
	v_cvt_pk_bf16_f32 v104, v108, v109
	v_cvt_pk_bf16_f32 v105, v110, v111
	v_pk_mul_f32 v[100:101], v[100:101], v[112:113] op_sel_hi:[1,0]
	v_cvt_pk_bf16_f32 v106, v106, v107
	v_cvt_pk_bf16_f32 v107, v116, v117
	global_store_dwordx4 v[114:115], v[104:107], off
	v_pk_mul_f32 v[102:103], v[102:103], v[112:113] op_sel_hi:[1,0]
	s_nop 0
	v_pk_mul_f32 v[104:105], v[98:99], v[112:113] op_sel_hi:[1,0]
	v_pk_mul_f32 v[98:99], v[96:97], v[112:113] op_sel_hi:[1,0]
	v_cvt_pk_bf16_f32 v96, v100, v101
	v_cvt_pk_bf16_f32 v97, v102, v103
	s_nop 0
	v_cvt_pk_bf16_f32 v98, v98, v99
	v_cvt_pk_bf16_f32 v99, v104, v105
	global_store_dwordx4 v[114:115], v[96:99], off offset:256
	s_nop 1
	v_or_b32_e32 v96, 32, v144
	v_ashrrev_i32_e32 v97, 31, v96
	v_mad_i64_i32 v[98:99], s[18:19], v96, s39, v[146:147]
	v_lshl_add_u64 v[96:97], v[96:97], 2, s[88:89]
	s_nop 1
	v_lshl_add_u64 v[98:99], v[98:99], 0, v[148:149]
	s_nop 1
	v_mov_b32_e32 v96, v237
	v_pk_mul_f32 v[94:95], v[94:95], v[96:97] op_sel_hi:[1,0]
	v_pk_mul_f32 v[92:93], v[92:93], v[96:97] op_sel_hi:[1,0]
	v_pk_mul_f32 v[100:101], v[90:91], v[96:97] op_sel_hi:[1,0]
	v_pk_mul_f32 v[90:91], v[88:89], v[96:97] op_sel_hi:[1,0]
	v_cvt_pk_bf16_f32 v88, v92, v93
	v_cvt_pk_bf16_f32 v89, v94, v95
	v_pk_mul_f32 v[84:85], v[84:85], v[96:97] op_sel_hi:[1,0]
	v_cvt_pk_bf16_f32 v90, v90, v91
	v_cvt_pk_bf16_f32 v91, v100, v101
	global_store_dwordx4 v[98:99], v[88:91], off
	v_pk_mul_f32 v[86:87], v[86:87], v[96:97] op_sel_hi:[1,0]
	s_nop 0
	v_pk_mul_f32 v[88:89], v[82:83], v[96:97] op_sel_hi:[1,0]
	v_pk_mul_f32 v[82:83], v[80:81], v[96:97] op_sel_hi:[1,0]
	v_cvt_pk_bf16_f32 v80, v84, v85
	v_cvt_pk_bf16_f32 v81, v86, v87
	s_nop 0
	v_cvt_pk_bf16_f32 v82, v82, v83
	v_cvt_pk_bf16_f32 v83, v88, v89
	global_store_dwordx4 v[98:99], v[80:83], off offset:256
	s_nop 1
	v_or_b32_e32 v80, 48, v144
	v_ashrrev_i32_e32 v81, 31, v80
	v_mad_i64_i32 v[82:83], s[18:19], v80, s39, v[146:147]
	v_lshl_add_u64 v[80:81], v[80:81], 2, s[88:89]
	s_nop 1
	v_lshl_add_u64 v[82:83], v[82:83], 0, v[148:149]
	s_nop 1
	v_mov_b32_e32 v80, v238
	v_pk_mul_f32 v[78:79], v[78:79], v[80:81] op_sel_hi:[1,0]
	v_pk_mul_f32 v[76:77], v[76:77], v[80:81] op_sel_hi:[1,0]
	v_pk_mul_f32 v[84:85], v[74:75], v[80:81] op_sel_hi:[1,0]
	v_pk_mul_f32 v[74:75], v[72:73], v[80:81] op_sel_hi:[1,0]
	v_cvt_pk_bf16_f32 v72, v76, v77
	v_cvt_pk_bf16_f32 v73, v78, v79
	v_pk_mul_f32 v[70:71], v[70:71], v[80:81] op_sel_hi:[1,0]
	v_cvt_pk_bf16_f32 v74, v74, v75
	v_cvt_pk_bf16_f32 v75, v84, v85
	global_store_dwordx4 v[82:83], v[72:75], off
	v_pk_mul_f32 v[68:69], v[68:69], v[80:81] op_sel_hi:[1,0]
	s_nop 0
	v_pk_mul_f32 v[72:73], v[66:67], v[80:81] op_sel_hi:[1,0]
	v_pk_mul_f32 v[66:67], v[64:65], v[80:81] op_sel_hi:[1,0]
	v_cvt_pk_bf16_f32 v64, v68, v69
	v_cvt_pk_bf16_f32 v65, v70, v71
	s_nop 0
	v_cvt_pk_bf16_f32 v66, v66, v67
	v_cvt_pk_bf16_f32 v67, v72, v73
	global_store_dwordx4 v[82:83], v[64:67], off offset:256
	s_nop 1
	s_nop 1
	v_mov_b32_e32 v66, v239
	v_pk_mul_f32 v[62:63], v[62:63], v[66:67] op_sel_hi:[1,0]
	v_add_u32_e32 v64, 0x80, v144
	v_mad_i64_i32 v[64:65], s[18:19], v64, s39, v[146:147]
	v_lshl_add_u64 v[64:65], v[64:65], 0, v[148:149]
	v_pk_mul_f32 v[60:61], v[60:61], v[66:67] op_sel_hi:[1,0]
	v_pk_mul_f32 v[68:69], v[58:59], v[66:67] op_sel_hi:[1,0]
	v_pk_mul_f32 v[58:59], v[56:57], v[66:67] op_sel_hi:[1,0]
	v_cvt_pk_bf16_f32 v56, v60, v61
	v_cvt_pk_bf16_f32 v57, v62, v63
	v_pk_mul_f32 v[54:55], v[54:55], v[66:67] op_sel_hi:[1,0]
	v_cvt_pk_bf16_f32 v58, v58, v59
	v_cvt_pk_bf16_f32 v59, v68, v69
	global_store_dwordx4 v[64:65], v[56:59], off
	v_pk_mul_f32 v[52:53], v[52:53], v[66:67] op_sel_hi:[1,0]
	s_nop 0
	v_pk_mul_f32 v[56:57], v[50:51], v[66:67] op_sel_hi:[1,0]
	v_pk_mul_f32 v[50:51], v[48:49], v[66:67] op_sel_hi:[1,0]
	v_cvt_pk_bf16_f32 v48, v52, v53
	v_cvt_pk_bf16_f32 v49, v54, v55
	s_nop 0
	v_cvt_pk_bf16_f32 v50, v50, v51
	v_cvt_pk_bf16_f32 v51, v56, v57
	global_store_dwordx4 v[64:65], v[48:51], off offset:256
	s_nop 1
	s_nop 1
	v_mov_b32_e32 v50, v240
	v_pk_mul_f32 v[46:47], v[46:47], v[50:51] op_sel_hi:[1,0]
	v_add_u32_e32 v48, 0x90, v144
	v_mad_i64_i32 v[48:49], s[18:19], v48, s39, v[146:147]
	v_lshl_add_u64 v[48:49], v[48:49], 0, v[148:149]
	v_pk_mul_f32 v[44:45], v[44:45], v[50:51] op_sel_hi:[1,0]
	v_pk_mul_f32 v[52:53], v[42:43], v[50:51] op_sel_hi:[1,0]
	v_pk_mul_f32 v[42:43], v[40:41], v[50:51] op_sel_hi:[1,0]
	v_cvt_pk_bf16_f32 v40, v44, v45
	v_cvt_pk_bf16_f32 v41, v46, v47
	v_pk_mul_f32 v[38:39], v[38:39], v[50:51] op_sel_hi:[1,0]
	v_cvt_pk_bf16_f32 v42, v42, v43
	v_cvt_pk_bf16_f32 v43, v52, v53
	global_store_dwordx4 v[48:49], v[40:43], off
	v_pk_mul_f32 v[36:37], v[36:37], v[50:51] op_sel_hi:[1,0]
	s_nop 0
	v_pk_mul_f32 v[40:41], v[34:35], v[50:51] op_sel_hi:[1,0]
	v_pk_mul_f32 v[34:35], v[32:33], v[50:51] op_sel_hi:[1,0]
	v_cvt_pk_bf16_f32 v32, v36, v37
	v_cvt_pk_bf16_f32 v33, v38, v39
	s_nop 0
	v_cvt_pk_bf16_f32 v34, v34, v35
	v_cvt_pk_bf16_f32 v35, v40, v41
	global_store_dwordx4 v[48:49], v[32:35], off offset:256
	s_nop 1
	s_nop 1
	v_mov_b32_e32 v34, v241
	v_pk_mul_f32 v[30:31], v[30:31], v[34:35] op_sel_hi:[1,0]
	v_add_u32_e32 v32, 0xa0, v144
	v_mad_i64_i32 v[32:33], s[18:19], v32, s39, v[146:147]
	v_lshl_add_u64 v[32:33], v[32:33], 0, v[148:149]
	v_pk_mul_f32 v[28:29], v[28:29], v[34:35] op_sel_hi:[1,0]
	v_pk_mul_f32 v[36:37], v[26:27], v[34:35] op_sel_hi:[1,0]
	v_pk_mul_f32 v[26:27], v[24:25], v[34:35] op_sel_hi:[1,0]
	v_cvt_pk_bf16_f32 v24, v28, v29
	v_cvt_pk_bf16_f32 v25, v30, v31
	v_pk_mul_f32 v[22:23], v[22:23], v[34:35] op_sel_hi:[1,0]
	v_cvt_pk_bf16_f32 v26, v26, v27
	v_cvt_pk_bf16_f32 v27, v36, v37
	global_store_dwordx4 v[32:33], v[24:27], off
	v_pk_mul_f32 v[20:21], v[20:21], v[34:35] op_sel_hi:[1,0]
	s_nop 0
	v_pk_mul_f32 v[24:25], v[18:19], v[34:35] op_sel_hi:[1,0]
	v_pk_mul_f32 v[18:19], v[16:17], v[34:35] op_sel_hi:[1,0]
	v_cvt_pk_bf16_f32 v16, v20, v21
	v_cvt_pk_bf16_f32 v17, v22, v23
	s_nop 0
	v_cvt_pk_bf16_f32 v18, v18, v19
	v_cvt_pk_bf16_f32 v19, v24, v25
	global_store_dwordx4 v[32:33], v[16:19], off offset:256
	s_nop 1
	s_nop 1
	v_mov_b32_e32 v18, v242
	v_pk_mul_f32 v[14:15], v[14:15], v[18:19] op_sel_hi:[1,0]
	v_add_u32_e32 v16, 0xb0, v144
	v_mad_i64_i32 v[16:17], s[18:19], v16, s39, v[146:147]
	v_lshl_add_u64 v[16:17], v[16:17], 0, v[148:149]
	v_pk_mul_f32 v[12:13], v[12:13], v[18:19] op_sel_hi:[1,0]
	v_pk_mul_f32 v[20:21], v[10:11], v[18:19] op_sel_hi:[1,0]
	v_pk_mul_f32 v[10:11], v[8:9], v[18:19] op_sel_hi:[1,0]
	v_cvt_pk_bf16_f32 v8, v12, v13
	v_cvt_pk_bf16_f32 v9, v14, v15
	s_mov_b64 s[18:19], -1
	v_cvt_pk_bf16_f32 v10, v10, v11
	v_cvt_pk_bf16_f32 v11, v20, v21
	global_store_dwordx4 v[16:17], v[8:11], off
	v_pk_mul_f32 v[6:7], v[6:7], v[18:19] op_sel_hi:[1,0]
	v_pk_mul_f32 v[4:5], v[4:5], v[18:19] op_sel_hi:[1,0]
	v_pk_mul_f32 v[8:9], v[2:3], v[18:19] op_sel_hi:[1,0]
	v_pk_mul_f32 v[2:3], v[0:1], v[18:19] op_sel_hi:[1,0]
	v_cvt_pk_bf16_f32 v0, v4, v5
	v_cvt_pk_bf16_f32 v1, v6, v7
	s_nop 0
	v_cvt_pk_bf16_f32 v2, v2, v3
	v_cvt_pk_bf16_f32 v3, v8, v9
	global_store_dwordx4 v[16:17], v[0:3], off offset:256
	s_cbranch_vccnz .LBB0_1556
	s_andn2_b64 vcc, exec, s[0:1]
	s_cbranch_vccnz .LBB0_1555
	s_barrier
	s_branch .LBB0_1555

.LBB0_1631:
	v_ashrrev_i32_e32 v128, 1, v140
	v_and_b32_e32 v129, -8, v128
	v_lshl_add_u32 v128, s0, 8, v141
	s_lshl_b32 s0, s4, 8
	v_readlane_b32 s1, v235, 37
	s_or_b32 s0, s1, s0
	v_add_u32_e32 v132, s0, v129
	v_ashrrev_i32_e32 v133, 31, v132
	s_movk_i32 s0, 0x1040
	v_mov_b64_e32 v[130:131], s[52:53]
	v_ashrrev_i32_e32 v129, 31, v128
	v_mad_i64_i32 v[134:135], s[4:5], v128, s0, v[130:131]
	v_lshlrev_b64 v[132:133], 1, v[132:133]
	v_lshl_add_u64 v[136:137], v[134:135], 0, v[132:133]
	v_lshl_add_u64 v[134:135], v[128:129], 2, s[88:89]
	global_load_dword v138, v[134:135], off
	global_load_dword v236, v[134:135], off offset:64
	global_load_dword v237, v[134:135], off offset:128
	global_load_dword v238, v[134:135], off offset:192
	global_load_dword v239, v[134:135], off offset:512
	global_load_dword v240, v[134:135], off offset:576
	global_load_dword v241, v[134:135], off offset:640
	global_load_dword v242, v[134:135], off offset:704
	s_waitcnt vmcnt(0)
	v_pk_mul_f32 v[126:127], v[126:127], v[138:139] op_sel_hi:[1,0]
	v_pk_mul_f32 v[124:125], v[124:125], v[138:139] op_sel_hi:[1,0]
	v_pk_mul_f32 v[140:141], v[122:123], v[138:139] op_sel_hi:[1,0]
	v_pk_mul_f32 v[122:123], v[120:121], v[138:139] op_sel_hi:[1,0]
	v_cvt_pk_bf16_f32 v120, v124, v125
	v_cvt_pk_bf16_f32 v121, v126, v127
	v_pk_mul_f32 v[116:117], v[116:117], v[138:139] op_sel_hi:[1,0]
	v_cvt_pk_bf16_f32 v122, v122, v123
	v_cvt_pk_bf16_f32 v123, v140, v141
	global_store_dwordx4 v[136:137], v[120:123], off
	v_pk_mul_f32 v[118:119], v[118:119], v[138:139] op_sel_hi:[1,0]
	s_nop 0
	v_pk_mul_f32 v[120:121], v[114:115], v[138:139] op_sel_hi:[1,0]
	v_pk_mul_f32 v[114:115], v[112:113], v[138:139] op_sel_hi:[1,0]
	v_cvt_pk_bf16_f32 v112, v116, v117
	v_cvt_pk_bf16_f32 v113, v118, v119
	s_nop 0
	v_cvt_pk_bf16_f32 v114, v114, v115
	v_cvt_pk_bf16_f32 v115, v120, v121
	global_store_dwordx4 v[136:137], v[112:115], off offset:256
	s_nop 1
	v_or_b32_e32 v112, 16, v128
	v_ashrrev_i32_e32 v113, 31, v112
	v_mad_i64_i32 v[114:115], s[4:5], v112, s0, v[130:131]
	v_lshl_add_u64 v[112:113], v[112:113], 2, s[88:89]
	s_nop 1
	v_lshl_add_u64 v[114:115], v[114:115], 0, v[132:133]
	s_nop 1
	v_mov_b32_e32 v112, v236
	v_pk_mul_f32 v[110:111], v[110:111], v[112:113] op_sel_hi:[1,0]
	v_pk_mul_f32 v[108:109], v[108:109], v[112:113] op_sel_hi:[1,0]
	v_pk_mul_f32 v[116:117], v[106:107], v[112:113] op_sel_hi:[1,0]
	v_pk_mul_f32 v[106:107], v[104:105], v[112:113] op_sel_hi:[1,0]
	v_cvt_pk_bf16_f32 v104, v108, v109
	v_cvt_pk_bf16_f32 v105, v110, v111
	v_pk_mul_f32 v[100:101], v[100:101], v[112:113] op_sel_hi:[1,0]
	v_cvt_pk_bf16_f32 v106, v106, v107
	v_cvt_pk_bf16_f32 v107, v116, v117
	global_store_dwordx4 v[114:115], v[104:107], off
	v_pk_mul_f32 v[102:103], v[102:103], v[112:113] op_sel_hi:[1,0]
	s_nop 0
	v_pk_mul_f32 v[104:105], v[98:99], v[112:113] op_sel_hi:[1,0]
	v_pk_mul_f32 v[98:99], v[96:97], v[112:113] op_sel_hi:[1,0]
	v_cvt_pk_bf16_f32 v96, v100, v101
	v_cvt_pk_bf16_f32 v97, v102, v103
	s_nop 0
	v_cvt_pk_bf16_f32 v98, v98, v99
	v_cvt_pk_bf16_f32 v99, v104, v105
	global_store_dwordx4 v[114:115], v[96:99], off offset:256
	s_nop 1
	v_or_b32_e32 v96, 32, v128
	v_ashrrev_i32_e32 v97, 31, v96
	v_mad_i64_i32 v[98:99], s[4:5], v96, s0, v[130:131]
	v_lshl_add_u64 v[96:97], v[96:97], 2, s[88:89]
	s_nop 1
	v_lshl_add_u64 v[98:99], v[98:99], 0, v[132:133]
	s_nop 1
	v_mov_b32_e32 v96, v237
	v_pk_mul_f32 v[94:95], v[94:95], v[96:97] op_sel_hi:[1,0]
	v_pk_mul_f32 v[92:93], v[92:93], v[96:97] op_sel_hi:[1,0]
	v_pk_mul_f32 v[100:101], v[90:91], v[96:97] op_sel_hi:[1,0]
	v_pk_mul_f32 v[90:91], v[88:89], v[96:97] op_sel_hi:[1,0]
	v_cvt_pk_bf16_f32 v88, v92, v93
	v_cvt_pk_bf16_f32 v89, v94, v95
	v_pk_mul_f32 v[84:85], v[84:85], v[96:97] op_sel_hi:[1,0]
	v_cvt_pk_bf16_f32 v90, v90, v91
	v_cvt_pk_bf16_f32 v91, v100, v101
	global_store_dwordx4 v[98:99], v[88:91], off
	v_pk_mul_f32 v[86:87], v[86:87], v[96:97] op_sel_hi:[1,0]
	s_nop 0
	v_pk_mul_f32 v[88:89], v[82:83], v[96:97] op_sel_hi:[1,0]
	v_pk_mul_f32 v[82:83], v[80:81], v[96:97] op_sel_hi:[1,0]
	v_cvt_pk_bf16_f32 v80, v84, v85
	v_cvt_pk_bf16_f32 v81, v86, v87
	s_nop 0
	v_cvt_pk_bf16_f32 v82, v82, v83
	v_cvt_pk_bf16_f32 v83, v88, v89
	global_store_dwordx4 v[98:99], v[80:83], off offset:256
	s_nop 1
	v_or_b32_e32 v80, 48, v128
	v_ashrrev_i32_e32 v81, 31, v80
	v_mad_i64_i32 v[82:83], s[4:5], v80, s0, v[130:131]
	v_lshl_add_u64 v[80:81], v[80:81], 2, s[88:89]
	s_nop 1
	v_lshl_add_u64 v[82:83], v[82:83], 0, v[132:133]
	s_nop 1
	v_mov_b32_e32 v80, v238
	v_pk_mul_f32 v[78:79], v[78:79], v[80:81] op_sel_hi:[1,0]
	v_pk_mul_f32 v[76:77], v[76:77], v[80:81] op_sel_hi:[1,0]
	v_pk_mul_f32 v[84:85], v[74:75], v[80:81] op_sel_hi:[1,0]
	v_pk_mul_f32 v[74:75], v[72:73], v[80:81] op_sel_hi:[1,0]
	v_cvt_pk_bf16_f32 v72, v76, v77
	v_cvt_pk_bf16_f32 v73, v78, v79
	v_pk_mul_f32 v[70:71], v[70:71], v[80:81] op_sel_hi:[1,0]
	v_cvt_pk_bf16_f32 v74, v74, v75
	v_cvt_pk_bf16_f32 v75, v84, v85
	global_store_dwordx4 v[82:83], v[72:75], off
	v_pk_mul_f32 v[68:69], v[68:69], v[80:81] op_sel_hi:[1,0]
	s_nop 0
	v_pk_mul_f32 v[72:73], v[66:67], v[80:81] op_sel_hi:[1,0]
	v_pk_mul_f32 v[66:67], v[64:65], v[80:81] op_sel_hi:[1,0]
	v_cvt_pk_bf16_f32 v64, v68, v69
	v_cvt_pk_bf16_f32 v65, v70, v71
	s_nop 0
	v_cvt_pk_bf16_f32 v66, v66, v67
	v_cvt_pk_bf16_f32 v67, v72, v73
	global_store_dwordx4 v[82:83], v[64:67], off offset:256
	s_nop 1
	s_nop 1
	v_mov_b32_e32 v66, v239
	v_pk_mul_f32 v[62:63], v[62:63], v[66:67] op_sel_hi:[1,0]
	v_add_u32_e32 v64, 0x80, v128
	v_mad_i64_i32 v[64:65], s[4:5], v64, s0, v[130:131]
	v_lshl_add_u64 v[64:65], v[64:65], 0, v[132:133]
	v_pk_mul_f32 v[60:61], v[60:61], v[66:67] op_sel_hi:[1,0]
	v_pk_mul_f32 v[68:69], v[58:59], v[66:67] op_sel_hi:[1,0]
	v_pk_mul_f32 v[58:59], v[56:57], v[66:67] op_sel_hi:[1,0]
	v_cvt_pk_bf16_f32 v56, v60, v61
	v_cvt_pk_bf16_f32 v57, v62, v63
	v_pk_mul_f32 v[54:55], v[54:55], v[66:67] op_sel_hi:[1,0]
	v_cvt_pk_bf16_f32 v58, v58, v59
	v_cvt_pk_bf16_f32 v59, v68, v69
	global_store_dwordx4 v[64:65], v[56:59], off
	v_pk_mul_f32 v[52:53], v[52:53], v[66:67] op_sel_hi:[1,0]
	s_nop 0
	v_pk_mul_f32 v[56:57], v[50:51], v[66:67] op_sel_hi:[1,0]
	v_pk_mul_f32 v[50:51], v[48:49], v[66:67] op_sel_hi:[1,0]
	v_cvt_pk_bf16_f32 v48, v52, v53
	v_cvt_pk_bf16_f32 v49, v54, v55
	s_nop 0
	v_cvt_pk_bf16_f32 v50, v50, v51
	v_cvt_pk_bf16_f32 v51, v56, v57
	global_store_dwordx4 v[64:65], v[48:51], off offset:256
	s_nop 1
	s_nop 1
	v_mov_b32_e32 v50, v240
	v_pk_mul_f32 v[46:47], v[46:47], v[50:51] op_sel_hi:[1,0]
	v_add_u32_e32 v48, 0x90, v128
	v_mad_i64_i32 v[48:49], s[4:5], v48, s0, v[130:131]
	v_lshl_add_u64 v[48:49], v[48:49], 0, v[132:133]
	v_pk_mul_f32 v[44:45], v[44:45], v[50:51] op_sel_hi:[1,0]
	v_pk_mul_f32 v[52:53], v[42:43], v[50:51] op_sel_hi:[1,0]
	v_pk_mul_f32 v[42:43], v[40:41], v[50:51] op_sel_hi:[1,0]
	v_cvt_pk_bf16_f32 v40, v44, v45
	v_cvt_pk_bf16_f32 v41, v46, v47
	v_pk_mul_f32 v[38:39], v[38:39], v[50:51] op_sel_hi:[1,0]
	v_cvt_pk_bf16_f32 v42, v42, v43
	v_cvt_pk_bf16_f32 v43, v52, v53
	global_store_dwordx4 v[48:49], v[40:43], off
	v_pk_mul_f32 v[36:37], v[36:37], v[50:51] op_sel_hi:[1,0]
	s_nop 0
	v_pk_mul_f32 v[40:41], v[34:35], v[50:51] op_sel_hi:[1,0]
	v_pk_mul_f32 v[34:35], v[32:33], v[50:51] op_sel_hi:[1,0]
	v_cvt_pk_bf16_f32 v32, v36, v37
	v_cvt_pk_bf16_f32 v33, v38, v39
	s_nop 0
	v_cvt_pk_bf16_f32 v34, v34, v35
	v_cvt_pk_bf16_f32 v35, v40, v41
	global_store_dwordx4 v[48:49], v[32:35], off offset:256
	s_nop 1
	s_nop 1
	v_mov_b32_e32 v34, v241
	v_pk_mul_f32 v[30:31], v[30:31], v[34:35] op_sel_hi:[1,0]
	v_add_u32_e32 v32, 0xa0, v128
	v_mad_i64_i32 v[32:33], s[4:5], v32, s0, v[130:131]
	v_lshl_add_u64 v[32:33], v[32:33], 0, v[132:133]
	v_pk_mul_f32 v[28:29], v[28:29], v[34:35] op_sel_hi:[1,0]
	v_pk_mul_f32 v[36:37], v[26:27], v[34:35] op_sel_hi:[1,0]
	v_pk_mul_f32 v[26:27], v[24:25], v[34:35] op_sel_hi:[1,0]
	v_cvt_pk_bf16_f32 v24, v28, v29
	v_cvt_pk_bf16_f32 v25, v30, v31
	v_pk_mul_f32 v[22:23], v[22:23], v[34:35] op_sel_hi:[1,0]
	v_cvt_pk_bf16_f32 v26, v26, v27
	v_cvt_pk_bf16_f32 v27, v36, v37
	global_store_dwordx4 v[32:33], v[24:27], off
	v_pk_mul_f32 v[20:21], v[20:21], v[34:35] op_sel_hi:[1,0]
	s_nop 0
	v_pk_mul_f32 v[24:25], v[18:19], v[34:35] op_sel_hi:[1,0]
	v_pk_mul_f32 v[18:19], v[16:17], v[34:35] op_sel_hi:[1,0]
	v_cvt_pk_bf16_f32 v16, v20, v21
	v_cvt_pk_bf16_f32 v17, v22, v23
	s_nop 0
	v_cvt_pk_bf16_f32 v18, v18, v19
	v_cvt_pk_bf16_f32 v19, v24, v25
	global_store_dwordx4 v[32:33], v[16:19], off offset:256
	s_nop 1
	s_nop 1
	v_mov_b32_e32 v18, v242
	v_pk_mul_f32 v[14:15], v[14:15], v[18:19] op_sel_hi:[1,0]
	v_add_u32_e32 v16, 0xb0, v128
	v_mad_i64_i32 v[16:17], s[0:1], v16, s0, v[130:131]
	v_lshl_add_u64 v[16:17], v[16:17], 0, v[132:133]
	v_pk_mul_f32 v[12:13], v[12:13], v[18:19] op_sel_hi:[1,0]
	v_pk_mul_f32 v[20:21], v[10:11], v[18:19] op_sel_hi:[1,0]
	v_pk_mul_f32 v[10:11], v[8:9], v[18:19] op_sel_hi:[1,0]
	v_cvt_pk_bf16_f32 v8, v12, v13
	v_cvt_pk_bf16_f32 v9, v14, v15
	v_pk_mul_f32 v[6:7], v[6:7], v[18:19] op_sel_hi:[1,0]
	v_cvt_pk_bf16_f32 v10, v10, v11
	v_cvt_pk_bf16_f32 v11, v20, v21
	global_store_dwordx4 v[16:17], v[8:11], off
	v_pk_mul_f32 v[4:5], v[4:5], v[18:19] op_sel_hi:[1,0]
	v_readlane_b32 s0, v235, 41
	v_pk_mul_f32 v[8:9], v[2:3], v[18:19] op_sel_hi:[1,0]
	v_pk_mul_f32 v[2:3], v[0:1], v[18:19] op_sel_hi:[1,0]
	v_cvt_pk_bf16_f32 v0, v4, v5
	v_cvt_pk_bf16_f32 v1, v6, v7
	v_readlane_b32 s1, v235, 42
	v_cvt_pk_bf16_f32 v2, v2, v3
	v_cvt_pk_bf16_f32 v3, v8, v9
	global_store_dwordx4 v[16:17], v[0:3], off offset:256
	s_waitcnt vmcnt(0)
	s_barrier
	s_waitcnt vmcnt(0)
	s_and_b64 vcc, exec, s[0:1]
	s_barrier
	s_cbranch_vccnz .LBB0_1645
	v_mbcnt_lo_u32_b32 v0, -1, 0
	v_mbcnt_hi_u32_b32 v0, -1, v0
	s_nop 0
	v_cmp_eq_u32_e32 vcc, 0, v0
	s_and_saveexec_b64 s[0:1], vcc
	s_cbranch_execz .LBB0_1644
	s_mov_b64 s[6:7], exec
	buffer_wbl2 sc1
	s_waitcnt vmcnt(0)
	s_waitcnt vmcnt(0)
	v_mbcnt_lo_u32_b32 v0, s6, 0
	s_add_u32 s4, s78, 0x3900
	v_mbcnt_hi_u32_b32 v0, s7, v0
	s_addc_u32 s5, s79, 0
	v_cmp_eq_u32_e32 vcc, 0, v0
	s_and_saveexec_b64 s[8:9], vcc
	s_cbranch_execz .LBB0_1635
	s_bcnt1_i32_b64 s6, s[6:7]
	v_mov_b32_e32 v0, 0
	v_mov_b32_e32 v1, s6
	global_atomic_add v0, v1, s[4:5]

.LBB0_2274:
	v_lshl_add_u32 v148, s19, 8, v154
	v_lshl_add_u32 v144, s18, 8, v152
	v_ashrrev_i32_e32 v149, 31, v148
	v_mov_b64_e32 v[146:147], s[52:53]
	v_ashrrev_i32_e32 v145, 31, v144
	v_mad_i64_i32 v[150:151], s[18:19], v144, s39, v[146:147]
	v_lshlrev_b64 v[148:149], 1, v[148:149]
	v_lshl_add_u64 v[158:159], v[150:151], 0, v[148:149]
	v_lshl_add_u64 v[150:151], v[144:145], 2, s[88:89]
	global_load_dword v160, v[150:151], off
	global_load_dword v236, v[150:151], off offset:64
	global_load_dword v237, v[150:151], off offset:128
	global_load_dword v238, v[150:151], off offset:192
	global_load_dword v239, v[150:151], off offset:512
	global_load_dword v240, v[150:151], off offset:576
	global_load_dword v241, v[150:151], off offset:640
	global_load_dword v242, v[150:151], off offset:704
	s_andn2_b64 vcc, exec, s[4:5]
	s_waitcnt vmcnt(0)
	v_pk_mul_f32 v[126:127], v[126:127], v[160:161] op_sel_hi:[1,0]
	v_pk_mul_f32 v[124:125], v[124:125], v[160:161] op_sel_hi:[1,0]
	v_pk_mul_f32 v[162:163], v[122:123], v[160:161] op_sel_hi:[1,0]
	v_pk_mul_f32 v[122:123], v[120:121], v[160:161] op_sel_hi:[1,0]
	v_cvt_pk_bf16_f32 v120, v124, v125
	v_cvt_pk_bf16_f32 v121, v126, v127
	v_pk_mul_f32 v[116:117], v[116:117], v[160:161] op_sel_hi:[1,0]
	v_cvt_pk_bf16_f32 v122, v122, v123
	v_cvt_pk_bf16_f32 v123, v162, v163
	global_store_dwordx4 v[158:159], v[120:123], off
	v_pk_mul_f32 v[118:119], v[118:119], v[160:161] op_sel_hi:[1,0]
	s_nop 0
	v_pk_mul_f32 v[120:121], v[114:115], v[160:161] op_sel_hi:[1,0]
	v_pk_mul_f32 v[114:115], v[112:113], v[160:161] op_sel_hi:[1,0]
	v_cvt_pk_bf16_f32 v112, v116, v117
	v_cvt_pk_bf16_f32 v113, v118, v119
	s_nop 0
	v_cvt_pk_bf16_f32 v114, v114, v115
	v_cvt_pk_bf16_f32 v115, v120, v121
	global_store_dwordx4 v[158:159], v[112:115], off offset:256
	s_nop 1
	v_or_b32_e32 v112, 16, v144
	v_ashrrev_i32_e32 v113, 31, v112
	v_mad_i64_i32 v[114:115], s[18:19], v112, s39, v[146:147]
	v_lshl_add_u64 v[112:113], v[112:113], 2, s[88:89]
	s_nop 1
	v_lshl_add_u64 v[114:115], v[114:115], 0, v[148:149]
	s_nop 1
	v_mov_b32_e32 v112, v236
	v_pk_mul_f32 v[110:111], v[110:111], v[112:113] op_sel_hi:[1,0]
	v_pk_mul_f32 v[108:109], v[108:109], v[112:113] op_sel_hi:[1,0]
	v_pk_mul_f32 v[116:117], v[106:107], v[112:113] op_sel_hi:[1,0]
	v_pk_mul_f32 v[106:107], v[104:105], v[112:113] op_sel_hi:[1,0]
	v_cvt_pk_bf16_f32 v104, v108, v109
	v_cvt_pk_bf16_f32 v105, v110, v111
	v_pk_mul_f32 v[100:101], v[100:101], v[112:113] op_sel_hi:[1,0]
	v_cvt_pk_bf16_f32 v106, v106, v107
	v_cvt_pk_bf16_f32 v107, v116, v117
	global_store_dwordx4 v[114:115], v[104:107], off
	v_pk_mul_f32 v[102:103], v[102:103], v[112:113] op_sel_hi:[1,0]
	s_nop 0
	v_pk_mul_f32 v[104:105], v[98:99], v[112:113] op_sel_hi:[1,0]
	v_pk_mul_f32 v[98:99], v[96:97], v[112:113] op_sel_hi:[1,0]
	v_cvt_pk_bf16_f32 v96, v100, v101
	v_cvt_pk_bf16_f32 v97, v102, v103
	s_nop 0
	v_cvt_pk_bf16_f32 v98, v98, v99
	v_cvt_pk_bf16_f32 v99, v104, v105
	global_store_dwordx4 v[114:115], v[96:99], off offset:256
	s_nop 1
	v_or_b32_e32 v96, 32, v144
	v_ashrrev_i32_e32 v97, 31, v96
	v_mad_i64_i32 v[98:99], s[18:19], v96, s39, v[146:147]
	v_lshl_add_u64 v[96:97], v[96:97], 2, s[88:89]
	s_nop 1
	v_lshl_add_u64 v[98:99], v[98:99], 0, v[148:149]
	s_nop 1
	v_mov_b32_e32 v96, v237
	v_pk_mul_f32 v[94:95], v[94:95], v[96:97] op_sel_hi:[1,0]
	v_pk_mul_f32 v[92:93], v[92:93], v[96:97] op_sel_hi:[1,0]
	v_pk_mul_f32 v[100:101], v[90:91], v[96:97] op_sel_hi:[1,0]
	v_pk_mul_f32 v[90:91], v[88:89], v[96:97] op_sel_hi:[1,0]
	v_cvt_pk_bf16_f32 v88, v92, v93
	v_cvt_pk_bf16_f32 v89, v94, v95
	v_pk_mul_f32 v[84:85], v[84:85], v[96:97] op_sel_hi:[1,0]
	v_cvt_pk_bf16_f32 v90, v90, v91
	v_cvt_pk_bf16_f32 v91, v100, v101
	global_store_dwordx4 v[98:99], v[88:91], off
	v_pk_mul_f32 v[86:87], v[86:87], v[96:97] op_sel_hi:[1,0]
	s_nop 0
	v_pk_mul_f32 v[88:89], v[82:83], v[96:97] op_sel_hi:[1,0]
	v_pk_mul_f32 v[82:83], v[80:81], v[96:97] op_sel_hi:[1,0]
	v_cvt_pk_bf16_f32 v80, v84, v85
	v_cvt_pk_bf16_f32 v81, v86, v87
	s_nop 0
	v_cvt_pk_bf16_f32 v82, v82, v83
	v_cvt_pk_bf16_f32 v83, v88, v89
	global_store_dwordx4 v[98:99], v[80:83], off offset:256
	s_nop 1
	v_or_b32_e32 v80, 48, v144
	v_ashrrev_i32_e32 v81, 31, v80
	v_mad_i64_i32 v[82:83], s[18:19], v80, s39, v[146:147]
	v_lshl_add_u64 v[80:81], v[80:81], 2, s[88:89]
	s_nop 1
	v_lshl_add_u64 v[82:83], v[82:83], 0, v[148:149]
	s_nop 1
	v_mov_b32_e32 v80, v238
	v_pk_mul_f32 v[78:79], v[78:79], v[80:81] op_sel_hi:[1,0]
	v_pk_mul_f32 v[76:77], v[76:77], v[80:81] op_sel_hi:[1,0]
	v_pk_mul_f32 v[84:85], v[74:75], v[80:81] op_sel_hi:[1,0]
	v_pk_mul_f32 v[74:75], v[72:73], v[80:81] op_sel_hi:[1,0]
	v_cvt_pk_bf16_f32 v72, v76, v77
	v_cvt_pk_bf16_f32 v73, v78, v79
	v_pk_mul_f32 v[70:71], v[70:71], v[80:81] op_sel_hi:[1,0]
	v_cvt_pk_bf16_f32 v74, v74, v75
	v_cvt_pk_bf16_f32 v75, v84, v85
	global_store_dwordx4 v[82:83], v[72:75], off
	v_pk_mul_f32 v[68:69], v[68:69], v[80:81] op_sel_hi:[1,0]
	s_nop 0
	v_pk_mul_f32 v[72:73], v[66:67], v[80:81] op_sel_hi:[1,0]
	v_pk_mul_f32 v[66:67], v[64:65], v[80:81] op_sel_hi:[1,0]
	v_cvt_pk_bf16_f32 v64, v68, v69
	v_cvt_pk_bf16_f32 v65, v70, v71
	s_nop 0
	v_cvt_pk_bf16_f32 v66, v66, v67
	v_cvt_pk_bf16_f32 v67, v72, v73
	global_store_dwordx4 v[82:83], v[64:67], off offset:256
	s_nop 1
	s_nop 1
	v_mov_b32_e32 v66, v239
	v_pk_mul_f32 v[62:63], v[62:63], v[66:67] op_sel_hi:[1,0]
	v_add_u32_e32 v64, 0x80, v144
	v_mad_i64_i32 v[64:65], s[18:19], v64, s39, v[146:147]
	v_lshl_add_u64 v[64:65], v[64:65], 0, v[148:149]
	v_pk_mul_f32 v[60:61], v[60:61], v[66:67] op_sel_hi:[1,0]
	v_pk_mul_f32 v[68:69], v[58:59], v[66:67] op_sel_hi:[1,0]
	v_pk_mul_f32 v[58:59], v[56:57], v[66:67] op_sel_hi:[1,0]
	v_cvt_pk_bf16_f32 v56, v60, v61
	v_cvt_pk_bf16_f32 v57, v62, v63
	v_pk_mul_f32 v[54:55], v[54:55], v[66:67] op_sel_hi:[1,0]
	v_cvt_pk_bf16_f32 v58, v58, v59
	v_cvt_pk_bf16_f32 v59, v68, v69
	global_store_dwordx4 v[64:65], v[56:59], off
	v_pk_mul_f32 v[52:53], v[52:53], v[66:67] op_sel_hi:[1,0]
	s_nop 0
	v_pk_mul_f32 v[56:57], v[50:51], v[66:67] op_sel_hi:[1,0]
	v_pk_mul_f32 v[50:51], v[48:49], v[66:67] op_sel_hi:[1,0]
	v_cvt_pk_bf16_f32 v48, v52, v53
	v_cvt_pk_bf16_f32 v49, v54, v55
	s_nop 0
	v_cvt_pk_bf16_f32 v50, v50, v51
	v_cvt_pk_bf16_f32 v51, v56, v57
	global_store_dwordx4 v[64:65], v[48:51], off offset:256
	s_nop 1
	s_nop 1
	v_mov_b32_e32 v50, v240
	v_pk_mul_f32 v[46:47], v[46:47], v[50:51] op_sel_hi:[1,0]
	v_add_u32_e32 v48, 0x90, v144
	v_mad_i64_i32 v[48:49], s[18:19], v48, s39, v[146:147]
	v_lshl_add_u64 v[48:49], v[48:49], 0, v[148:149]
	v_pk_mul_f32 v[44:45], v[44:45], v[50:51] op_sel_hi:[1,0]
	v_pk_mul_f32 v[52:53], v[42:43], v[50:51] op_sel_hi:[1,0]
	v_pk_mul_f32 v[42:43], v[40:41], v[50:51] op_sel_hi:[1,0]
	v_cvt_pk_bf16_f32 v40, v44, v45
	v_cvt_pk_bf16_f32 v41, v46, v47
	v_pk_mul_f32 v[38:39], v[38:39], v[50:51] op_sel_hi:[1,0]
	v_cvt_pk_bf16_f32 v42, v42, v43
	v_cvt_pk_bf16_f32 v43, v52, v53
	global_store_dwordx4 v[48:49], v[40:43], off
	v_pk_mul_f32 v[36:37], v[36:37], v[50:51] op_sel_hi:[1,0]
	s_nop 0
	v_pk_mul_f32 v[40:41], v[34:35], v[50:51] op_sel_hi:[1,0]
	v_pk_mul_f32 v[34:35], v[32:33], v[50:51] op_sel_hi:[1,0]
	v_cvt_pk_bf16_f32 v32, v36, v37
	v_cvt_pk_bf16_f32 v33, v38, v39
	s_nop 0
	v_cvt_pk_bf16_f32 v34, v34, v35
	v_cvt_pk_bf16_f32 v35, v40, v41
	global_store_dwordx4 v[48:49], v[32:35], off offset:256
	s_nop 1
	s_nop 1
	v_mov_b32_e32 v34, v241
	v_pk_mul_f32 v[30:31], v[30:31], v[34:35] op_sel_hi:[1,0]
	v_add_u32_e32 v32, 0xa0, v144
	v_mad_i64_i32 v[32:33], s[18:19], v32, s39, v[146:147]
	v_lshl_add_u64 v[32:33], v[32:33], 0, v[148:149]
	v_pk_mul_f32 v[28:29], v[28:29], v[34:35] op_sel_hi:[1,0]
	v_pk_mul_f32 v[36:37], v[26:27], v[34:35] op_sel_hi:[1,0]
	v_pk_mul_f32 v[26:27], v[24:25], v[34:35] op_sel_hi:[1,0]
	v_cvt_pk_bf16_f32 v24, v28, v29
	v_cvt_pk_bf16_f32 v25, v30, v31
	v_pk_mul_f32 v[22:23], v[22:23], v[34:35] op_sel_hi:[1,0]
	v_cvt_pk_bf16_f32 v26, v26, v27
	v_cvt_pk_bf16_f32 v27, v36, v37
	global_store_dwordx4 v[32:33], v[24:27], off
	v_pk_mul_f32 v[20:21], v[20:21], v[34:35] op_sel_hi:[1,0]
	s_nop 0
	v_pk_mul_f32 v[24:25], v[18:19], v[34:35] op_sel_hi:[1,0]
	v_pk_mul_f32 v[18:19], v[16:17], v[34:35] op_sel_hi:[1,0]
	v_cvt_pk_bf16_f32 v16, v20, v21
	v_cvt_pk_bf16_f32 v17, v22, v23
	s_nop 0
	v_cvt_pk_bf16_f32 v18, v18, v19
	v_cvt_pk_bf16_f32 v19, v24, v25
	global_store_dwordx4 v[32:33], v[16:19], off offset:256
	s_nop 1
	s_nop 1
	v_mov_b32_e32 v18, v242
	v_pk_mul_f32 v[14:15], v[14:15], v[18:19] op_sel_hi:[1,0]
	v_add_u32_e32 v16, 0xb0, v144
	v_mad_i64_i32 v[16:17], s[18:19], v16, s39, v[146:147]
	v_lshl_add_u64 v[16:17], v[16:17], 0, v[148:149]
	v_pk_mul_f32 v[12:13], v[12:13], v[18:19] op_sel_hi:[1,0]
	v_pk_mul_f32 v[20:21], v[10:11], v[18:19] op_sel_hi:[1,0]
	v_pk_mul_f32 v[10:11], v[8:9], v[18:19] op_sel_hi:[1,0]
	v_cvt_pk_bf16_f32 v8, v12, v13
	v_cvt_pk_bf16_f32 v9, v14, v15
	s_mov_b64 s[18:19], -1
	v_cvt_pk_bf16_f32 v10, v10, v11
	v_cvt_pk_bf16_f32 v11, v20, v21
	global_store_dwordx4 v[16:17], v[8:11], off
	v_pk_mul_f32 v[6:7], v[6:7], v[18:19] op_sel_hi:[1,0]
	v_pk_mul_f32 v[4:5], v[4:5], v[18:19] op_sel_hi:[1,0]
	v_pk_mul_f32 v[8:9], v[2:3], v[18:19] op_sel_hi:[1,0]
	v_pk_mul_f32 v[2:3], v[0:1], v[18:19] op_sel_hi:[1,0]
	v_cvt_pk_bf16_f32 v0, v4, v5
	v_cvt_pk_bf16_f32 v1, v6, v7
	s_nop 0
	v_cvt_pk_bf16_f32 v2, v2, v3
	v_cvt_pk_bf16_f32 v3, v8, v9
	global_store_dwordx4 v[16:17], v[0:3], off offset:256
	s_cbranch_vccnz .LBB0_2265
	s_andn2_b64 vcc, exec, s[0:1]
	s_cbranch_vccnz .LBB0_2264
	s_barrier
	s_branch .LBB0_2264

.LBB0_2340:
	v_lshl_add_u32 v128, s4, 8, v141
	v_ashrrev_i32_e32 v129, 31, v128
	v_lshl_add_u64 v[130:131], v[128:129], 2, s[88:89]
	global_load_dword v136, v[130:131], off
	global_load_dword v236, v[130:131], off offset:64
	global_load_dword v237, v[130:131], off offset:128
	global_load_dword v238, v[130:131], off offset:192
	global_load_dword v239, v[130:131], off offset:512
	global_load_dword v240, v[130:131], off offset:576
	global_load_dword v241, v[130:131], off offset:640
	global_load_dword v242, v[130:131], off offset:704
	v_ashrrev_i32_e32 v129, 1, v140
	s_lshl_b32 s1, s0, 8
	v_readlane_b32 s4, v235, 37
	v_and_b32_e32 v129, -8, v129
	s_or_b32 s1, s4, s1
	v_add_u32_e32 v134, s1, v129
	s_movk_i32 s0, 0x1040
	v_mov_b64_e32 v[132:133], s[52:53]
	v_ashrrev_i32_e32 v135, 31, v134
	v_mad_i64_i32 v[138:139], s[4:5], v128, s0, v[132:133]
	v_or_b32_e32 v140, 16, v128
	v_lshlrev_b64 v[134:135], 1, v[134:135]
	v_ashrrev_i32_e32 v141, 31, v140
	v_lshl_add_u64 v[138:139], v[138:139], 0, v[134:135]
	v_lshl_add_u64 v[142:143], v[140:141], 2, s[88:89]
	s_waitcnt vmcnt(0)
	v_pk_mul_f32 v[126:127], v[126:127], v[136:137] op_sel_hi:[1,0]
	v_pk_mul_f32 v[124:125], v[124:125], v[136:137] op_sel_hi:[1,0]
	v_pk_mul_f32 v[122:123], v[122:123], v[136:137] op_sel_hi:[1,0]
	v_pk_mul_f32 v[120:121], v[120:121], v[136:137] op_sel_hi:[1,0]
	v_pk_mul_f32 v[118:119], v[118:119], v[136:137] op_sel_hi:[1,0]
	v_pk_mul_f32 v[116:117], v[116:117], v[136:137] op_sel_hi:[1,0]
	v_pk_mul_f32 v[144:145], v[114:115], v[136:137] op_sel_hi:[1,0]
	v_pk_mul_f32 v[136:137], v[112:113], v[136:137] op_sel_hi:[1,0]
	v_cvt_pk_bf16_f32 v112, v124, v125
	v_cvt_pk_bf16_f32 v113, v126, v127
	v_cvt_pk_bf16_f32 v114, v120, v121
	v_cvt_pk_bf16_f32 v115, v122, v123
	global_store_dwordx4 v[138:139], v[112:115], off
	s_nop 1
	v_cvt_pk_bf16_f32 v112, v116, v117
	v_cvt_pk_bf16_f32 v113, v118, v119
	v_cvt_pk_bf16_f32 v114, v136, v137
	v_cvt_pk_bf16_f32 v115, v144, v145
	global_store_dwordx4 v[138:139], v[112:115], off offset:256
	s_nop 1
	v_mad_i64_i32 v[116:117], s[4:5], v140, s0, v[132:133]
	v_or_b32_e32 v114, 32, v128
	v_ashrrev_i32_e32 v115, 31, v114
	v_lshl_add_u64 v[116:117], v[116:117], 0, v[134:135]
	v_lshl_add_u64 v[118:119], v[114:115], 2, s[88:89]
	s_nop 1
	v_mov_b32_e32 v112, v236
	v_pk_mul_f32 v[110:111], v[110:111], v[112:113] op_sel_hi:[1,0]
	v_pk_mul_f32 v[108:109], v[108:109], v[112:113] op_sel_hi:[1,0]
	v_pk_mul_f32 v[106:107], v[106:107], v[112:113] op_sel_hi:[1,0]
	v_pk_mul_f32 v[104:105], v[104:105], v[112:113] op_sel_hi:[1,0]
	v_pk_mul_f32 v[102:103], v[102:103], v[112:113] op_sel_hi:[1,0]
	v_pk_mul_f32 v[100:101], v[100:101], v[112:113] op_sel_hi:[1,0]
	v_pk_mul_f32 v[120:121], v[98:99], v[112:113] op_sel_hi:[1,0]
	v_pk_mul_f32 v[112:113], v[96:97], v[112:113] op_sel_hi:[1,0]
	v_cvt_pk_bf16_f32 v96, v108, v109
	v_cvt_pk_bf16_f32 v97, v110, v111
	v_cvt_pk_bf16_f32 v98, v104, v105
	v_cvt_pk_bf16_f32 v99, v106, v107
	global_store_dwordx4 v[116:117], v[96:99], off
	s_nop 1
	v_cvt_pk_bf16_f32 v96, v100, v101
	v_cvt_pk_bf16_f32 v97, v102, v103
	v_cvt_pk_bf16_f32 v98, v112, v113
	v_cvt_pk_bf16_f32 v99, v120, v121
	global_store_dwordx4 v[116:117], v[96:99], off offset:256
	s_nop 1
	v_mad_i64_i32 v[100:101], s[4:5], v114, s0, v[132:133]
	v_or_b32_e32 v98, 48, v128
	v_ashrrev_i32_e32 v99, 31, v98
	v_lshl_add_u64 v[100:101], v[100:101], 0, v[134:135]
	v_lshl_add_u64 v[102:103], v[98:99], 2, s[88:89]
	s_nop 1
	v_mov_b32_e32 v96, v237
	v_pk_mul_f32 v[94:95], v[94:95], v[96:97] op_sel_hi:[1,0]
	v_pk_mul_f32 v[92:93], v[92:93], v[96:97] op_sel_hi:[1,0]
	v_pk_mul_f32 v[90:91], v[90:91], v[96:97] op_sel_hi:[1,0]
	v_pk_mul_f32 v[88:89], v[88:89], v[96:97] op_sel_hi:[1,0]
	v_pk_mul_f32 v[82:83], v[82:83], v[96:97] op_sel_hi:[1,0]
	v_pk_mul_f32 v[80:81], v[80:81], v[96:97] op_sel_hi:[1,0]
	v_pk_mul_f32 v[104:105], v[74:75], v[96:97] op_sel_hi:[1,0]
	v_pk_mul_f32 v[96:97], v[72:73], v[96:97] op_sel_hi:[1,0]
	v_cvt_pk_bf16_f32 v72, v92, v93
	v_cvt_pk_bf16_f32 v73, v94, v95
	v_cvt_pk_bf16_f32 v74, v88, v89
	v_cvt_pk_bf16_f32 v75, v90, v91
	global_store_dwordx4 v[100:101], v[72:75], off
	s_nop 1
	v_cvt_pk_bf16_f32 v72, v80, v81
	v_cvt_pk_bf16_f32 v73, v82, v83
	v_cvt_pk_bf16_f32 v74, v96, v97
	v_cvt_pk_bf16_f32 v75, v104, v105
	global_store_dwordx4 v[100:101], v[72:75], off offset:256
	s_nop 1
	s_nop 1
	v_mov_b32_e32 v72, v238
	v_pk_mul_f32 v[80:81], v[86:87], v[72:73] op_sel_hi:[1,0]
	v_mad_i64_i32 v[74:75], s[4:5], v98, s0, v[132:133]
	v_lshl_add_u64 v[74:75], v[74:75], 0, v[134:135]
	v_pk_mul_f32 v[82:83], v[84:85], v[72:73] op_sel_hi:[1,0]
	v_pk_mul_f32 v[78:79], v[78:79], v[72:73] op_sel_hi:[1,0]
	v_pk_mul_f32 v[76:77], v[76:77], v[72:73] op_sel_hi:[1,0]
	v_pk_mul_f32 v[70:71], v[70:71], v[72:73] op_sel_hi:[1,0]
	v_pk_mul_f32 v[68:69], v[68:69], v[72:73] op_sel_hi:[1,0]
	v_pk_mul_f32 v[84:85], v[66:67], v[72:73] op_sel_hi:[1,0]
	v_pk_mul_f32 v[72:73], v[64:65], v[72:73] op_sel_hi:[1,0]
	v_cvt_pk_bf16_f32 v64, v82, v83
	v_cvt_pk_bf16_f32 v65, v80, v81
	v_cvt_pk_bf16_f32 v66, v76, v77
	v_cvt_pk_bf16_f32 v67, v78, v79
	global_store_dwordx4 v[74:75], v[64:67], off
	s_nop 1
	v_cvt_pk_bf16_f32 v64, v68, v69
	v_cvt_pk_bf16_f32 v65, v70, v71
	v_cvt_pk_bf16_f32 v66, v72, v73
	v_cvt_pk_bf16_f32 v67, v84, v85
	global_store_dwordx4 v[74:75], v[64:67], off offset:256
	s_nop 1
	s_nop 0
	v_add_u32_e32 v65, 0x80, v128
	v_mad_i64_i32 v[66:67], s[4:5], v65, s0, v[132:133]
	v_lshl_add_u64 v[66:67], v[66:67], 0, v[134:135]
	s_nop 1
	v_mov_b32_e32 v64, v239
	v_pk_mul_f32 v[62:63], v[62:63], v[64:65] op_sel_hi:[1,0]
	v_pk_mul_f32 v[60:61], v[60:61], v[64:65] op_sel_hi:[1,0]
	v_pk_mul_f32 v[58:59], v[58:59], v[64:65] op_sel_hi:[1,0]
	v_pk_mul_f32 v[56:57], v[56:57], v[64:65] op_sel_hi:[1,0]
	v_pk_mul_f32 v[54:55], v[54:55], v[64:65] op_sel_hi:[1,0]
	v_pk_mul_f32 v[52:53], v[52:53], v[64:65] op_sel_hi:[1,0]
	v_pk_mul_f32 v[68:69], v[50:51], v[64:65] op_sel_hi:[1,0]
	v_pk_mul_f32 v[64:65], v[48:49], v[64:65] op_sel_hi:[1,0]
	v_cvt_pk_bf16_f32 v48, v60, v61
	v_cvt_pk_bf16_f32 v49, v62, v63
	v_cvt_pk_bf16_f32 v50, v56, v57
	v_cvt_pk_bf16_f32 v51, v58, v59
	global_store_dwordx4 v[66:67], v[48:51], off
	s_nop 1
	v_cvt_pk_bf16_f32 v48, v52, v53
	v_cvt_pk_bf16_f32 v49, v54, v55
	v_cvt_pk_bf16_f32 v50, v64, v65
	v_cvt_pk_bf16_f32 v51, v68, v69
	global_store_dwordx4 v[66:67], v[48:51], off offset:256
	s_nop 1
	s_nop 0
	v_add_u32_e32 v49, 0x90, v128
	v_mad_i64_i32 v[50:51], s[4:5], v49, s0, v[132:133]
	v_lshl_add_u64 v[50:51], v[50:51], 0, v[134:135]
	s_nop 1
	v_mov_b32_e32 v48, v240
	v_pk_mul_f32 v[46:47], v[46:47], v[48:49] op_sel_hi:[1,0]
	v_pk_mul_f32 v[44:45], v[44:45], v[48:49] op_sel_hi:[1,0]
	v_pk_mul_f32 v[42:43], v[42:43], v[48:49] op_sel_hi:[1,0]
	v_pk_mul_f32 v[40:41], v[40:41], v[48:49] op_sel_hi:[1,0]
	v_pk_mul_f32 v[38:39], v[38:39], v[48:49] op_sel_hi:[1,0]
	v_pk_mul_f32 v[36:37], v[36:37], v[48:49] op_sel_hi:[1,0]
	v_pk_mul_f32 v[52:53], v[34:35], v[48:49] op_sel_hi:[1,0]
	v_pk_mul_f32 v[48:49], v[32:33], v[48:49] op_sel_hi:[1,0]
	v_cvt_pk_bf16_f32 v32, v44, v45
	v_cvt_pk_bf16_f32 v33, v46, v47
	v_cvt_pk_bf16_f32 v34, v40, v41
	v_cvt_pk_bf16_f32 v35, v42, v43
	global_store_dwordx4 v[50:51], v[32:35], off
	s_nop 1
	v_cvt_pk_bf16_f32 v32, v36, v37
	v_cvt_pk_bf16_f32 v33, v38, v39
	v_cvt_pk_bf16_f32 v34, v48, v49
	v_cvt_pk_bf16_f32 v35, v52, v53
	global_store_dwordx4 v[50:51], v[32:35], off offset:256
	s_nop 1
	s_nop 0
	v_add_u32_e32 v33, 0xa0, v128
	v_mad_i64_i32 v[34:35], s[4:5], v33, s0, v[132:133]
	v_lshl_add_u64 v[34:35], v[34:35], 0, v[134:135]
	s_nop 1
	v_mov_b32_e32 v32, v241
	v_pk_mul_f32 v[30:31], v[30:31], v[32:33] op_sel_hi:[1,0]
	v_pk_mul_f32 v[28:29], v[28:29], v[32:33] op_sel_hi:[1,0]
	v_pk_mul_f32 v[26:27], v[26:27], v[32:33] op_sel_hi:[1,0]
	v_pk_mul_f32 v[24:25], v[24:25], v[32:33] op_sel_hi:[1,0]
	v_pk_mul_f32 v[22:23], v[22:23], v[32:33] op_sel_hi:[1,0]
	v_pk_mul_f32 v[20:21], v[20:21], v[32:33] op_sel_hi:[1,0]
	v_pk_mul_f32 v[36:37], v[18:19], v[32:33] op_sel_hi:[1,0]
	v_pk_mul_f32 v[32:33], v[16:17], v[32:33] op_sel_hi:[1,0]
	v_cvt_pk_bf16_f32 v16, v28, v29
	v_cvt_pk_bf16_f32 v17, v30, v31
	v_cvt_pk_bf16_f32 v18, v24, v25
	v_cvt_pk_bf16_f32 v19, v26, v27
	global_store_dwordx4 v[34:35], v[16:19], off
	s_nop 1
	v_cvt_pk_bf16_f32 v16, v20, v21
	v_cvt_pk_bf16_f32 v17, v22, v23
	v_cvt_pk_bf16_f32 v18, v32, v33
	v_cvt_pk_bf16_f32 v19, v36, v37
	global_store_dwordx4 v[34:35], v[16:19], off offset:256
	s_nop 1
	s_nop 0
	v_add_u32_e32 v17, 0xb0, v128
	v_mad_i64_i32 v[18:19], s[0:1], v17, s0, v[132:133]
	v_lshl_add_u64 v[18:19], v[18:19], 0, v[134:135]
	v_readlane_b32 s0, v235, 41
	v_readlane_b32 s1, v235, 42
	s_and_b64 vcc, exec, s[0:1]
	s_nop 1
	v_mov_b32_e32 v16, v242
	v_pk_mul_f32 v[14:15], v[14:15], v[16:17] op_sel_hi:[1,0]
	v_pk_mul_f32 v[12:13], v[12:13], v[16:17] op_sel_hi:[1,0]
	v_pk_mul_f32 v[10:11], v[10:11], v[16:17] op_sel_hi:[1,0]
	v_pk_mul_f32 v[8:9], v[8:9], v[16:17] op_sel_hi:[1,0]
	v_pk_mul_f32 v[6:7], v[6:7], v[16:17] op_sel_hi:[1,0]
	v_pk_mul_f32 v[4:5], v[4:5], v[16:17] op_sel_hi:[1,0]
	v_pk_mul_f32 v[20:21], v[2:3], v[16:17] op_sel_hi:[1,0]
	v_pk_mul_f32 v[16:17], v[0:1], v[16:17] op_sel_hi:[1,0]
	v_cvt_pk_bf16_f32 v0, v12, v13
	v_cvt_pk_bf16_f32 v1, v14, v15
	v_cvt_pk_bf16_f32 v2, v8, v9
	v_cvt_pk_bf16_f32 v3, v10, v11
	global_store_dwordx4 v[18:19], v[0:3], off
	s_nop 1
	v_cvt_pk_bf16_f32 v0, v4, v5
	v_cvt_pk_bf16_f32 v1, v6, v7
	v_cvt_pk_bf16_f32 v2, v16, v17
	v_cvt_pk_bf16_f32 v3, v20, v21
	global_store_dwordx4 v[18:19], v[0:3], off offset:256
	s_waitcnt vmcnt(0)
	s_barrier
	s_waitcnt vmcnt(0)
	s_barrier
	s_cbranch_vccnz .LBB0_2354
	v_mbcnt_lo_u32_b32 v0, -1, 0
	v_mbcnt_hi_u32_b32 v0, -1, v0
	s_nop 0
	v_cmp_eq_u32_e32 vcc, 0, v0
	s_and_saveexec_b64 s[0:1], vcc
	s_cbranch_execz .LBB0_2353
	s_mov_b64 s[6:7], exec
	buffer_wbl2 sc1
	s_waitcnt vmcnt(0)
	s_waitcnt vmcnt(0)
	v_mbcnt_lo_u32_b32 v0, s6, 0
	s_add_u32 s4, s78, 0x3a00
	v_mbcnt_hi_u32_b32 v0, s7, v0
	s_addc_u32 s5, s79, 0
	v_cmp_eq_u32_e32 vcc, 0, v0
	s_and_saveexec_b64 s[8:9], vcc
	s_cbranch_execz .LBB0_2344
	s_bcnt1_i32_b64 s6, s[6:7]
	v_mov_b32_e32 v0, 0
	v_mov_b32_e32 v1, s6
	global_atomic_add v0, v1, s[4:5]
